# gdn_prep conv weights cached in spare LDS (6 KB) instead of 12 serialized L2 round trips per item; plus earlier gdn_prep/scan/LN-epilogue edits
# speedup vs baseline: 1.0260x; 1.0191x over previous
; #define LAS __attribute__((address_space(3)))
;     const int tid = c.tid, lane = c.lane, wid = c.wid;
;     const int b = item >> 9, h = (item >> 6) & 7, n = item & 63;
;     const int tok0 = b * SEQ + n * 64;
;     LAS float* qc = (LAS float*)c.lds; LAS float* kc = qc + 64 * 68; LAS float* vc = kc + 64 * 68; LAS float* Lm = vc + 64 * 68; LAS float* rhs = Lm + 64 * 68; LAS float* gcs = rhs + 64 * 132; LAS float* bet = gcs + 64;
;     LAS bf16_t* KH = (LAS bf16_t*)(bet + 64); LAS bf16_t* KL = KH + 64 * 72; LAS bf16_t* QH = KL + 64 * 72; LAS bf16_t* QL = QH + 64 * 72;
;     unsigned char* gout = gbase + (size_t)item * GSLOT;
; #pragma unroll
;     for (int which = 0; which < 3; ++which) {
;         const int t = tid >> 3, cg8 = tid & 7; const int col = which * 512 + h * 64 + cg8 * 8;
;         float acc[8];
; #pragma unroll
;         for (int e = 0; e < 8; ++e) acc[e] = 0.f;
; #pragma unroll
;         for (int j = 0; j < 4; ++j) { const int sp = n * 64 + t - 3 + j; const float ok = sp >= 0 ? 1.f : 0.f;
;             const u32x4 xv = xin[which * 4 + j];
;             const f32x4 w0 = *(const f32x4*)(conv_w + j * 1536 + col) * ok, w1 = *(const f32x4*)(conv_w + j * 1536 + col + 4) * ok;
;             acc[0] += w0[0] * bflo(xv.x); acc[1] += w0[1] * bfhi(xv.x); acc[2] += w0[2] * bflo(xv.y); acc[3] += w0[3] * bfhi(xv.y);
;             acc[4] += w1[0] * bflo(xv.z); acc[5] += w1[1] * bfhi(xv.z); acc[6] += w1[2] * bflo(xv.w); acc[7] += w1[3] * bfhi(xv.w); }
; #pragma unroll
;         for (int e = 0; e < 8; ++e) acc[e] = silu_f(acc[e]);
;         if (which == 2) { LAS float* dst = vc + t * 68 + cg8 * 8; *(LAS f32x4*)dst = (f32x4){acc[0], acc[1], acc[2], acc[3]}; *(LAS f32x4*)(dst + 4) = (f32x4){acc[4], acc[5], acc[6], acc[7]}; }
;         else {
;             float ss = (acc[0] * acc[0] + acc[1] * acc[1]) + (acc[2] * acc[2] + acc[3] * acc[3]) + (acc[4] * acc[4] + acc[5] * acc[5]) + (acc[6] * acc[6] + acc[7] * acc[7]);
;             ss += __shfl_xor(ss, 1); ss += __shfl_xor(ss, 2); ss += __shfl_xor(ss, 4);
;             const float sc = (which ? 1.0f : 0.125f) * __builtin_amdgcn_rsqf(ss + 1e-6f);
;             const f32x4 y0 = (f32x4){acc[0], acc[1], acc[2], acc[3]} * sc, y1 = (f32x4){acc[4], acc[5], acc[6], acc[7]} * sc;
;             LAS float* dst = (which ? kc : qc) + t * 68 + cg8 * 8; *(LAS f32x4*)dst = y0; *(LAS f32x4*)(dst + 4) = y1;
.LBB0_431:
	v_mbcnt_lo_u32_b32 v2, -1, 0
	v_mbcnt_hi_u32_b32 v2, -1, v2
	v_and_b32_e32 v4, 64, v2
	v_xor_b32_e32 v3, 1, v2
	v_add_u32_e32 v5, 64, v4
	v_cmp_lt_i32_e32 vcc, v3, v5
	s_add_u32 s0, s34, 0x10000
	v_writelane_b32 v247, s0, 33
	v_cndmask_b32_e32 v3, v2, v3, vcc
	v_lshlrev_b32_e32 v101, 2, v3
	v_xor_b32_e32 v3, 2, v2
	v_cmp_lt_i32_e32 vcc, v3, v5
	s_addc_u32 s0, s35, 0
	s_add_u32 s71, s34, 0x9800000
	v_cndmask_b32_e32 v3, v2, v3, vcc
	v_lshlrev_b32_e32 v102, 2, v3
	v_xor_b32_e32 v3, 4, v2
	v_cmp_lt_i32_e32 vcc, v3, v5
	s_addc_u32 s74, s35, 0
	s_cmp_lg_u32 s94, 3
	v_cndmask_b32_e32 v3, v2, v3, vcc
	v_lshlrev_b32_e32 v103, 2, v3
	v_add_u32_e32 v3, -1, v2
	v_cmp_lt_i32_e32 vcc, v3, v4
	v_writelane_b32 v247, s0, 34
	s_cselect_b64 s[0:1], -1, 0
	v_cndmask_b32_e32 v3, v3, v2, vcc
	v_lshlrev_b32_e32 v104, 2, v3
	v_add_u32_e32 v3, -2, v2
	v_cmp_lt_i32_e32 vcc, v3, v4
	s_cmp_lg_u32 s94, 4
	s_cselect_b64 s[96:97], -1, 0
	v_cndmask_b32_e32 v3, v3, v2, vcc
	v_lshlrev_b32_e32 v105, 2, v3
	v_add_u32_e32 v3, -4, v2
	v_cmp_lt_i32_e32 vcc, v3, v4
	s_cmp_lg_u32 s94, 5
	s_cselect_b64 s[2:3], -1, 0
	v_cndmask_b32_e32 v3, v3, v2, vcc
	v_lshlrev_b32_e32 v106, 2, v3
	v_add_u32_e32 v3, -8, v2
	v_cmp_lt_i32_e32 vcc, v3, v4
	v_writelane_b32 v247, s2, 35
	v_lshrrev_b32_e32 v110, 3, v152
	v_cndmask_b32_e32 v3, v3, v2, vcc
	v_writelane_b32 v247, s3, 36
	s_mov_b32 s2, 0x1de00
	v_lshlrev_b32_e32 v107, 2, v3
	v_add_u32_e32 v3, -16, v2
	s_add_i32 s16, s2, 0x100
	s_mov_b32 s2, 0x20200
	v_cmp_lt_i32_e32 vcc, v3, v4
	s_add_i32 s17, s2, 0x100
	s_mov_b32 s2, 0x19600
	v_cndmask_b32_e32 v3, v3, v2, vcc
	s_add_i32 s18, s2, 0x100
	s_mov_b32 s2, 0x1ba00
	v_lshlrev_b32_e32 v108, 2, v3
	v_subrev_u32_e32 v3, 32, v2
	s_add_i32 s19, s2, 0x100
	v_readlane_b32 s29, v247, 26
	v_cmp_lt_i32_e32 vcc, v3, v4
	s_cmp_lt_u32 s29, 64
	s_mov_b32 s2, 0x19400
	s_mov_b32 s3, 0x19500
	v_cndmask_b32_e32 v2, v3, v2, vcc
	s_cselect_b64 s[20:21], -1, 0
	s_addk_i32 s2, 0x100
	s_addk_i32 s3, 0x100
	s_bfe_u32 s26, s29, 0x10007
	s_bfe_u32 s27, s29, 0x10006
	v_lshlrev_b32_e32 v109, 2, v2
	v_lshlrev_b32_e32 v2, 3, v152
	s_cmp_le_u32 s26, s27
	v_and_b32_e32 v111, 56, v2
	v_mul_u32_u24_e32 v5, 0x48, v110
	s_cselect_b64 s[22:23], -1, 0
	s_cmpk_gt_u32 s29, 0xff
	v_lshlrev_b32_e32 v5, 1, v5
	v_lshlrev_b32_e32 v82, 1, v111
	s_cselect_b64 s[24:25], -1, 0
	s_cmpk_lt_u32 s29, 0x100
	v_add3_u32 v113, s16, v5, v82
	v_add3_u32 v114, s17, v5, v82
	v_add3_u32 v115, s18, v5, v82
	v_add3_u32 v116, s19, v5, v82
	v_lshlrev_b32_e32 v5, 2, v202
	v_and_b32_e32 v6, 31, v152
	s_cselect_b32 s16, s18, s16
	s_cselect_b32 s17, s19, s17
	s_lshl_b32 s28, s26, 5
	v_add_u32_e32 v117, s2, v5
	v_add_u32_e32 v118, s3, v5
	v_lshrrev_b32_e32 v5, 5, v202
	v_or_b32_e32 v7, s28, v6
	v_lshl_or_b32 v9, s27, 5, v6
	v_mul_u32_u24_e32 v7, 0x48, v7
	v_lshlrev_b32_e32 v8, 3, v5
	v_mul_u32_u24_e32 v10, 0x48, v9
	v_add_lshl_u32 v7, v7, v8, 1
	v_add_lshl_u32 v8, v10, v8, 1
	v_lshl_or_b32 v5, v5, 2, s28
	v_add_u32_e32 v121, s16, v8
	v_add_u32_e32 v122, s17, v8
	v_cmp_gt_u32_e64 s[16:17], v5, v9
	v_or_b32_e32 v10, 1, v5
	v_lshl_add_u32 v132, v10, 2, s2
	v_writelane_b32 v247, s16, 37
	v_add_u32_e32 v8, 32, v7
	v_add_u32_e32 v123, s18, v8
	v_writelane_b32 v247, s17, 38
	v_cmp_lt_u32_e64 s[16:17], v5, v9
	v_add_u32_e32 v124, s19, v8
	v_add_u32_e32 v8, 64, v7
	v_writelane_b32 v247, s16, 39
	v_add_u32_e32 v125, s18, v8
	v_add_u32_e32 v126, s19, v8
	v_writelane_b32 v247, s17, 40
	v_cmp_lt_u32_e64 s[16:17], v10, v9
	v_or_b32_e32 v10, 2, v5
	v_lshl_add_u32 v133, v10, 2, s2
	v_writelane_b32 v247, s16, 41
	v_lshl_add_u32 v131, v5, 2, s2
	v_mul_u32_u24_e32 v8, 0x110, v5
	v_writelane_b32 v247, s17, 42
	v_cmp_gt_u32_e64 s[16:17], v10, v9
	v_lshlrev_b32_e32 v86, 4, v202
	v_lshrrev_b32_e32 v16, 2, v152
	v_writelane_b32 v247, s16, 43
	v_and_b32_e32 v24, 0x60, v110
	v_and_or_b32 v15, v110, 32, v6
	v_writelane_b32 v247, s17, 44
	v_cmp_lt_u32_e64 s[16:17], v10, v9
	v_or_b32_e32 v10, 3, v5
	v_lshl_add_u32 v134, v10, 2, s2
	v_writelane_b32 v247, s16, 45
	v_and_b32_e32 v16, 48, v16
	v_and_b32_e32 v17, 4, v110
	v_writelane_b32 v247, s17, 46
	v_cmp_gt_u32_e64 s[16:17], v10, v9
	s_movk_i32 s76, 0x210
	v_or_b32_e32 v6, v24, v6
	v_writelane_b32 v247, s16, 47
	v_add_u32_e32 v119, s18, v7
	v_add_u32_e32 v120, s19, v7
	v_writelane_b32 v247, s17, 48
	v_cmp_lt_u32_e64 s[16:17], v10, v9
	v_or_b32_e32 v10, 8, v5
	v_lshl_add_u32 v135, v10, 2, s2
	v_writelane_b32 v247, s16, 49
	v_add_u32_e32 v7, 0x60, v7
	v_or_b32_e32 v18, v16, v17
	v_writelane_b32 v247, s17, 50
	v_cmp_gt_u32_e64 s[16:17], v10, v9
	v_lshlrev_b32_e32 v16, 2, v16
	v_lshlrev_b32_e32 v17, 2, v17
	v_writelane_b32 v247, s16, 51
	v_add_u32_e32 v127, s18, v7
	v_add_u32_e32 v128, s19, v7
	v_writelane_b32 v247, s17, 52
	v_cmp_lt_u32_e64 s[16:17], v10, v9
	v_or_b32_e32 v10, 9, v5
	v_lshl_add_u32 v136, v10, 2, s2
	v_writelane_b32 v247, s16, 53
	v_lshlrev_b32_e32 v7, 2, v9
	v_mov_b32_e32 v2, 0x100
	v_writelane_b32 v247, s17, 54
	v_cmp_gt_u32_e64 s[16:17], v10, v9
	v_lshlrev_b32_e32 v90, 4, v152
	v_lshl_add_u32 v3, v111, 2, v2
	v_writelane_b32 v247, s16, 55
	v_lshlrev_b32_e32 v19, 2, v18
	v_add_u32_e32 v20, 0x100, v19
	v_writelane_b32 v247, s17, 56
	v_cmp_lt_u32_e64 s[16:17], v10, v9
	v_or_b32_e32 v10, 10, v5
	v_lshl_add_u32 v137, v10, 2, s2
	v_writelane_b32 v247, s16, 57
	v_add_u32_e32 v166, s2, v19
	v_lshrrev_b32_e32 v19, 4, v202
	v_writelane_b32 v247, s17, 58
	v_cmp_gt_u32_e64 s[16:17], v10, v9
	v_lshrrev_b32_e32 v170, 7, v152
	v_lshlrev_b32_e32 v21, 2, v15
	v_writelane_b32 v247, s16, 59
	v_lshlrev_b32_e32 v23, 2, v19
	s_movk_i32 s75, 0x110
	v_writelane_b32 v247, s17, 60
	v_cmp_lt_u32_e64 s[16:17], v10, v9
	v_or_b32_e32 v10, 11, v5
; #define LAS __attribute__((address_space(3)))
; DI float fexp2(float x) { return __builtin_amdgcn_exp2f(x); }
; DI int crow(int r, int hi) { return (r & 3) + 8 * (r >> 2) + 4 * hi; }
;     ...
;             const int i = 32 * it + l31; const float gi = gcs[i], bi = bet[i];
; #pragma unroll
;             for (int r = 0; r < 16; ++r) { const int j = 32 * jt + crow(r, hi); const float d = fexp2((gi - gcs[j]) * 1.4426950408889634f);
;                 if (isqk) acc[r] = (j <= i) ? acc[r] * d : 0.f; else Lm[j * 68 + i] = (j < i) ? bi * acc[r] * d : 0.f; }
;             if (isqk) {
; #pragma unroll
;                 for (int sx = 0; sx < 2; ++sx) { const bf16x8 pk = pack8(acc, sx); *(u32x4*)(gout + 2 * 8192 + ((it * 4 + 2 * jt + sx) * 64 + lane) * 16) = __builtin_bit_cast(u32x4, pk); } }
;             else if (jt == it) {
;                 const int bb = 2 * jt + ((lane >> 4) & 1), col = lane & 15;
;                 float y[16];
; #pragma unroll
;                 for (int ii = 0; ii < 16; ++ii) y[ii] = (ii == col) ? 1.f : 0.f;
; #pragma unroll
;                 for (int j = 0; j < 15; ++j) { const float yj = y[j];
; #pragma unroll
;                     for (int q4 = (j + 1) / 4; q4 < 4; ++q4) { const f32x4 l4 = *(const LAS f32x4*)(Lm + (16 * bb + j) * 68 + 16 * bb + 4 * q4);
; #pragma unroll
;                         for (int e = 0; e < 4; ++e) if (4 * q4 + e > j) y[4 * q4 + e] -= l4[e] * yj; } }
; #pragma unroll
;                 for (int ii = 0; ii < 16; ++ii) DIV[bb * 320 + ii * 20 + col] = y[ii];
	v_lshl_add_u32 v138, v10, 2, s2
	v_writelane_b32 v247, s16, 61
	v_mul_u32_u24_e32 v4, 0x110, v110
	v_mov_b32_e32 v83, 0
	v_writelane_b32 v247, s17, 62
	v_cmp_gt_u32_e64 s[16:17], v10, v9
	v_add_u32_e32 v129, s2, v7
	v_add_u32_e32 v130, s3, v7
	v_writelane_b32 v247, s16, 63
	v_add_u32_e32 v7, 0x100, v7
	v_add_u32_e32 v22, 0x100, v21
	v_writelane_b32 v246, s17, 0
	v_cmp_lt_u32_e64 s[16:17], v10, v9
	v_or_b32_e32 v10, 16, v5
	v_lshl_add_u32 v139, v10, 2, s2
	v_writelane_b32 v246, s16, 1
	v_add_u32_e32 v165, s2, v21
	v_mul_u32_u24_e32 v15, 0x110, v15
	v_writelane_b32 v246, s17, 2
	v_cmp_gt_u32_e64 s[16:17], v10, v9
	v_mul_u32_u24_e32 v18, 0x110, v18
	s_movk_i32 s77, 0x1ff
	v_writelane_b32 v246, s16, 3
	s_mov_b32 s41, 0
	v_mad_u32_u24 v112, v110, s75, v3
	v_writelane_b32 v246, s17, 4
	v_cmp_lt_u32_e64 s[16:17], v10, v9
	v_or_b32_e32 v10, 17, v5
	v_lshl_add_u32 v140, v10, 2, s2
	v_writelane_b32 v246, s16, 5
	v_cmp_eq_u32_e64 s[4:5], 0, v202
	v_cmp_gt_u32_e64 s[6:7], 2, v202
	v_writelane_b32 v246, s17, 6
	v_cmp_gt_u32_e64 s[16:17], v10, v9
	v_cmp_gt_u32_e64 s[8:9], 4, v202
	v_cmp_gt_u32_e64 s[10:11], 8, v202
	v_writelane_b32 v246, s16, 7
	v_cmp_gt_u32_e64 s[12:13], 16, v202
	v_cmp_gt_u32_e64 s[14:15], 32, v202
	v_writelane_b32 v246, s17, 8
	v_cmp_lt_u32_e64 s[16:17], v10, v9
	v_or_b32_e32 v10, 18, v5
	v_lshl_add_u32 v141, v10, 2, s2
	v_writelane_b32 v246, s16, 9
	v_lshl_add_u64 v[84:85], s[36:37], 0, v[82:83]
	v_mov_b32_e32 v89, v83
	v_writelane_b32 v246, s17, 10
	v_cmp_gt_u32_e64 s[16:17], v10, v9
	v_mov_b32_e32 v87, v83
	v_and_b32_e32 v92, 0x1ff0, v90
	v_writelane_b32 v246, s16, 11
	v_mov_b32_e32 v93, v83
	v_add_u32_e32 v167, 32, v166
	v_writelane_b32 v246, s17, 12
	v_cmp_lt_u32_e64 s[16:17], v10, v9
	v_or_b32_e32 v10, 19, v5
	v_lshl_add_u32 v142, v10, 2, s2
	v_writelane_b32 v246, s16, 13
	v_mov_b32_e32 v91, v83
	v_cmp_lt_u32_e64 s[82:83], s77, v152
	v_writelane_b32 v246, s17, 14
	v_cmp_gt_u32_e64 s[16:17], v10, v9
	v_add_u32_e32 v173, 0x200, v152
	s_mov_b32 s78, 0xbfb8aa3b
	v_writelane_b32 v246, s16, 15
	v_add_u32_e32 v176, v3, v4
	s_mov_b32 s79, 0x42ce8ed0
	v_writelane_b32 v246, s17, 16
	v_cmp_lt_u32_e64 s[16:17], v10, v9
	v_or_b32_e32 v10, 24, v5
	v_lshl_add_u32 v143, v10, 2, s2
	v_writelane_b32 v246, s16, 17
	s_mov_b32 s95, 0xc2ce8ed0
	v_mov_b32_e32 v177, 0x3ecc95a3
	v_writelane_b32 v246, s17, 18
	v_cmp_gt_u32_e64 s[16:17], v10, v9
	v_add_u32_e32 v180, v22, v18
	v_add_u32_e32 v181, v20, v15
	v_writelane_b32 v246, s16, 19
	v_mov_b32_e32 v193, 0x7f800000
	v_add_u32_e32 v194, v7, v8
	v_writelane_b32 v246, s17, 20
	v_cmp_lt_u32_e64 s[16:17], v10, v9
	v_or_b32_e32 v10, 25, v5
	v_lshl_add_u32 v144, v10, 2, s2
	v_writelane_b32 v246, s16, 21
	s_nop 1
	v_writelane_b32 v246, s17, 22
	v_cmp_gt_u32_e64 s[16:17], v10, v9
	s_nop 1
	v_writelane_b32 v246, s16, 23
	s_nop 1
	v_writelane_b32 v246, s17, 24
	v_cmp_lt_u32_e64 s[16:17], v10, v9
	v_or_b32_e32 v10, 26, v5
	v_or_b32_e32 v5, 27, v5
	v_writelane_b32 v246, s16, 25
	v_lshl_add_u32 v145, v10, 2, s2
	v_lshl_add_u32 v146, v5, 2, s2
	v_writelane_b32 v246, s17, 26
	v_cmp_gt_u32_e64 s[16:17], v10, v9
	s_nop 1
	v_writelane_b32 v246, s16, 27
	s_nop 1
	v_writelane_b32 v246, s17, 28
	v_cmp_lt_u32_e64 s[16:17], v10, v9
	v_and_b32_e32 v10, 15, v152
	v_cmp_eq_u32_e32 vcc, 0, v10
	v_writelane_b32 v246, s16, 29
	v_lshlrev_b32_e32 v12, 2, v10
	v_cndmask_b32_e64 v147, 0, 1.0, vcc
	v_writelane_b32 v246, s17, 30
	v_cmp_gt_u32_e64 s[16:17], v5, v9
	v_cmp_eq_u32_e32 vcc, 1, v10
	s_nop 0
	v_writelane_b32 v246, s16, 31
	v_cndmask_b32_e64 v148, 0, 1.0, vcc
	v_cmp_eq_u32_e32 vcc, 2, v10
	v_writelane_b32 v246, s17, 32
	v_cmp_lt_u32_e64 s[16:17], v5, v9
	v_cndmask_b32_e64 v149, 0, 1.0, vcc
	v_cmp_eq_u32_e32 vcc, 3, v10
	v_writelane_b32 v246, s16, 33
	v_lshrrev_b32_e32 v5, 4, v152
	v_cndmask_b32_e64 v150, 0, 1.0, vcc
	v_writelane_b32 v246, s17, 34
	s_bfe_u32 s16, s29, 0x20006
	s_brev_b32 s16, s16
	s_lshr_b32 s16, s16, 19
	s_cmp_eq_u32 s26, s27
	v_cmp_eq_u32_e32 vcc, 4, v10
	v_or_b32_e32 v88, s16, v86
	s_cselect_b64 s[16:17], -1, 0
	v_cndmask_b32_e64 v151, 0, 1.0, vcc
	v_cmp_eq_u32_e32 vcc, 5, v10
; #define LAS __attribute__((address_space(3)))
;     ...
;     LAS float* qc = (LAS float*)c.lds; LAS float* kc = qc + 64 * 68; LAS float* vc = kc + 64 * 68; LAS float* Lm = vc + 64 * 68; LAS float* rhs = Lm + 64 * 68; LAS float* gcs = rhs + 64 * 132; LAS float* bet = gcs + 64;
;     LAS bf16_t* KH = (LAS bf16_t*)(bet + 64); LAS bf16_t* KL = KH + 64 * 72; LAS bf16_t* QH = KL + 64 * 72; LAS bf16_t* QL = QH + 64 * 72;
;     unsigned char* gout = gbase + (size_t)item * GSLOT;
; #pragma unroll
;     for (int which = 0; which < 3; ++which) {
;         const int t = tid >> 3, cg8 = tid & 7; const int col = which * 512 + h * 64 + cg8 * 8;
;         float acc[8];
; #pragma unroll
;         for (int e = 0; e < 8; ++e) acc[e] = 0.f;
; #pragma unroll
;         for (int j = 0; j < 4; ++j) { const int sp = n * 64 + t - 3 + j; const float ok = sp >= 0 ? 1.f : 0.f;
;             const u32x4 xv = xin[which * 4 + j];
;             const f32x4 w0 = *(const f32x4*)(conv_w + j * 1536 + col) * ok, w1 = *(const f32x4*)(conv_w + j * 1536 + col + 4) * ok;
	v_writelane_b32 v246, s16, 35
	v_bfe_u32 v9, v152, 4, 1
	v_cndmask_b32_e64 v153, 0, 1.0, vcc
	v_cmp_eq_u32_e32 vcc, 6, v10
	v_writelane_b32 v246, s17, 36
	s_mov_b32 s17, 0x11000
	v_cndmask_b32_e64 v154, 0, 1.0, vcc
	v_cmp_eq_u32_e32 vcc, 7, v10
	s_addk_i32 s17, 0x100
	v_mov_b32_e32 v25, s17
	v_cndmask_b32_e64 v155, 0, 1.0, vcc
	v_cmp_eq_u32_e32 vcc, 8, v10
	v_mad_u32_u24 v6, v6, s76, v25
	v_readlane_b32 s16, v247, 25
	v_cndmask_b32_e64 v156, 0, 1.0, vcc
	v_cmp_eq_u32_e32 vcc, 9, v10
	v_add3_u32 v169, v6, v16, v17
	v_lshlrev_b32_e32 v16, 1, v152
	v_cndmask_b32_e64 v157, 0, 1.0, vcc
	v_cmp_eq_u32_e32 vcc, 10, v10
	v_and_or_b32 v9, s16, 2, v9
	s_mov_b32 s16, 0x22600
	v_cndmask_b32_e64 v158, 0, 1.0, vcc
	v_cmp_eq_u32_e32 vcc, 11, v10
	v_and_b32_e32 v5, 4, v5
	v_and_b32_e32 v6, 0x80, v152
	v_cndmask_b32_e64 v159, 0, 1.0, vcc
	v_cmp_eq_u32_e32 vcc, 12, v10
	v_and_b32_e32 v16, 0x7c, v16
	v_lshl_add_u32 v2, v9, 6, v2
	v_cndmask_b32_e64 v160, 0, 1.0, vcc
	v_cmp_eq_u32_e32 vcc, 13, v10
	v_mul_u32_u24_e32 v11, 0x1100, v9
	v_mul_u32_u24_e32 v9, 0x500, v9
	s_addk_i32 s16, 0x100
	v_add3_u32 v6, s17, v6, v16
	v_and_b32_e32 v16, 16, v90
	v_or_b32_e32 v25, 1, v5
	v_or_b32_e32 v27, 2, v5
	v_or_b32_e32 v29, 3, v5
	v_cndmask_b32_e64 v161, 0, 1.0, vcc
	v_cmp_eq_u32_e32 vcc, 14, v10
	v_add3_u32 v164, s16, v9, v12
	v_and_b32_e32 v9, 0x7f, v152
	s_and_b32 s18, s29, 0xffffffc0
	v_or3_b32 v17, v5, v16, v24
	v_or3_b32 v26, v16, v25, v24
	v_or3_b32 v28, v16, v27, v24
	v_or3_b32 v30, v16, v29, v24
	v_or_b32_e32 v16, 8, v16
	v_cndmask_b32_e64 v162, 0, 1.0, vcc
	v_cmp_eq_u32_e32 vcc, 15, v10
	v_cmp_lt_u32_e64 s[80:81], 63, v9
	v_lshlrev_b32_e32 v9, 2, v9
	s_add_i32 s18, s17, s18
	v_mul_u32_u24_e32 v10, 0x50, v10
	v_or3_b32 v5, v5, v16, v24
	v_or3_b32 v25, v25, v16, v24
	v_or3_b32 v27, v27, v16, v24
	v_or3_b32 v16, v29, v16, v24
	v_lshlrev_b32_e32 v24, 2, v170
	v_add_u32_e32 v13, 0x100, v9
	v_add_u32_e32 v14, s17, v9
	v_add_u32_e32 v21, s18, v12
	v_add_u32_e32 v12, 0x100, v12
	v_add3_u32 v168, s16, v10, v23
	v_mul_u32_u24_e32 v10, 0x840, v19
	v_mul_u32_u24_e32 v23, 0x210, v19
	v_mul_u32_u24_e32 v19, 0x110, v19
	v_mul_u32_u24_e32 v17, 0x210, v17
	v_mul_u32_u24_e32 v26, 0x210, v26
	v_mul_u32_u24_e32 v28, 0x210, v28
	v_mul_u32_u24_e32 v30, 0x210, v30
	v_mul_u32_u24_e32 v5, 0x210, v5
	v_mul_u32_u24_e32 v25, 0x210, v25
	v_mul_u32_u24_e32 v27, 0x210, v27
	v_mul_u32_u24_e32 v16, 0x210, v16
	v_add_u32_e32 v171, s3, v24
	v_mul_u32_u24_e32 v29, 0x110, v170
	v_add_u32_e32 v172, s2, v24
	v_mul_u32_u24_e32 v24, 0x210, v170
	s_mov_b32 s2, 0x194fc
	v_cndmask_b32_e64 v163, 0, 1.0, vcc
	v_add_u32_e32 v174, 0x4300, v9
	v_or_b32_e32 v175, 0x11000, v9
	s_mov_b64 s[28:29], 0x4000
	s_mov_b32 s26, 0xc2b17218
	s_mov_b32 s27, 0x3fb8aa3b
	s_mov_b32 s16, 0x42b17218
	s_add_i32 s17, s2, 0x100
	s_movk_i32 s18, 0x1a00
	v_add_u32_e32 v178, v2, v11
	v_add_u32_e32 v179, v14, v24
	v_add_u32_e32 v182, v21, v23
	v_add_u32_e32 v183, v21, v10
	v_add_u32_e32 v184, v12, v19
	v_add_u32_e32 v185, v6, v17
	v_add_u32_e32 v186, v6, v26
	v_add_u32_e32 v187, v6, v28
	v_add_u32_e32 v188, v6, v30
	v_add_u32_e32 v189, v6, v5
	v_add_u32_e32 v190, v6, v25
	v_add_u32_e32 v191, v6, v27
	v_add_u32_e32 v192, v6, v16
	v_add_u32_e32 v195, v13, v29
	v_and_b32_e32 v240, 15, v152
	v_lshlrev_b32_e32 v240, 4, v240
	v_bfe_u32 v241, v152, 4, 2
	v_bfe_u32 v242, v152, 6, 2
	v_lshrrev_b32_e32 v243, 8, v152
	v_cmp_gt_u32_e32 vcc, 3, v241
	s_and_saveexec_b64 s[98:99], vcc
	s_bfe_u32 s100, s70, 0x30006
	v_lshlrev_b32_e32 v237, 2, v243
	v_xor_b32_e32 v237, s100, v237
	v_mul_u32_u24_e32 v236, 0x1800, v242
	v_lshl_add_u32 v236, v241, 11, v236
	v_add_u32_e32 v236, v236, v240
	v_lshl_add_u32 v236, v237, 8, v236
	v_mul_u32_u24_e32 v237, 0xc00, v243
	v_mul_u32_u24_e32 v242, 0x300, v242
	v_add_u32_e32 v237, v237, v242
	v_lshl_add_u32 v237, v241, 8, v237
	v_add_u32_e32 v237, v237, v240
	v_add_u32_e32 v243, 0x24100, v237
	global_load_dwordx4 v[236:239], v236, s[48:49]
	s_waitcnt vmcnt(0)
	ds_write_b128 v243, v[236:239]
	s_mov_b64 exec, s[98:99]
	s_waitcnt lgkmcnt(0)
	s_barrier
	s_mov_b32 s2, s70
	s_branch .LBB0_434

; #define LAS __attribute__((address_space(3)))
; DI float bflo(unsigned w) { return __uint_as_float(w << 16); }
; DI float bfhi(unsigned w) { return __uint_as_float(w & 0xffff0000u); }
; DI float silu_f(float g) { return g * frcp(1.f + fexp2(-1.4426950408889634f * g)); }
;     ...
;     for (int which = 0; which < 3; ++which) {
;         const int t = tid >> 3, cg8 = tid & 7; const int col = which * 512 + h * 64 + cg8 * 8;
;         float acc[8];
; #pragma unroll
;         for (int e = 0; e < 8; ++e) acc[e] = 0.f;
; #pragma unroll
;         for (int j = 0; j < 4; ++j) { const int sp = n * 64 + t - 3 + j; const float ok = sp >= 0 ? 1.f : 0.f;
;             const u32x4 xv = xin[which * 4 + j];
;             const f32x4 w0 = *(const f32x4*)(conv_w + j * 1536 + col) * ok, w1 = *(const f32x4*)(conv_w + j * 1536 + col + 4) * ok;
;             acc[0] += w0[0] * bflo(xv.x); acc[1] += w0[1] * bfhi(xv.x); acc[2] += w0[2] * bflo(xv.y); acc[3] += w0[3] * bfhi(xv.y);
;             acc[4] += w1[0] * bflo(xv.z); acc[5] += w1[1] * bfhi(xv.z); acc[6] += w1[2] * bflo(xv.w); acc[7] += w1[3] * bfhi(xv.w); }
; #pragma unroll
;         for (int e = 0; e < 8; ++e) acc[e] = silu_f(acc[e]);
;         if (which == 2) { LAS float* dst = vc + t * 68 + cg8 * 8; *(LAS f32x4*)dst = (f32x4){acc[0], acc[1], acc[2], acc[3]}; *(LAS f32x4*)(dst + 4) = (f32x4){acc[4], acc[5], acc[6], acc[7]}; }
;         else {
;             float ss = (acc[0] * acc[0] + acc[1] * acc[1]) + (acc[2] * acc[2] + acc[3] * acc[3]) + (acc[4] * acc[4] + acc[5] * acc[5]) + (acc[6] * acc[6] + acc[7] * acc[7]);
;             ss += __shfl_xor(ss, 1); ss += __shfl_xor(ss, 2); ss += __shfl_xor(ss, 4);
.LBB0_434:
	s_lshl_b32 s19, s2, 6
	s_and_b32 s19, s19, 0xfc0
	v_add_u32_e32 v2, s19, v110
	v_cmp_lt_u32_e32 vcc, 2, v2
	s_bfe_u32 s3, s2, 0x30006
	s_bfe_u32 s100, s70, 0x30006
	s_xor_b32 s100, s100, s3
	s_mul_i32 s100, s100, 0x300
	v_lshlrev_b32_e32 v255, 2, v111
	v_add_u32_e32 v255, s100, v255
	v_add_u32_e32 v255, 0x24100, v255
	s_movk_i32 s19, 0x1000
	v_cndmask_b32_e64 v26, 0, 1.0, vcc
	v_cmp_lt_u32_e32 vcc, 1, v2
	s_mov_b64 s[42:43], 0x1800
	s_waitcnt vmcnt(0)
	v_lshlrev_b32_e32 v208, 16, v54
	v_cndmask_b32_e64 v24, 0, 1.0, vcc
	v_cmp_eq_u32_e32 vcc, 0, v2
	v_lshlrev_b32_e32 v2, 2, v111
	v_lshl_or_b32 v82, s3, 8, v2
	ds_read_b128 v[18:21], v255 offset:0
	ds_read_b128 v[2:5], v255 offset:16
	v_lshl_add_u64 v[14:15], s[48:49], 0, v[82:83]
	v_cndmask_b32_e64 v22, 1.0, 0, vcc
	v_and_b32_e32 v209, 0xffff0000, v54
	s_waitcnt lgkmcnt(0)
	v_pk_mul_f32 v[18:19], v[26:27], v[18:19] op_sel_hi:[0,1]
	s_waitcnt lgkmcnt(0)
	v_pk_mul_f32 v[10:11], v[2:3], v[26:27] op_sel_hi:[1,0]
	v_add_co_u32_e32 v2, vcc, s19, v14
	v_pk_mul_f32 v[8:9], v[4:5], v[26:27] op_sel_hi:[1,0]
	v_lshl_add_u64 v[4:5], v[14:15], 0, s[42:43]
	v_addc_co_u32_e32 v3, vcc, 0, v15, vcc
	ds_read_b128 v[28:31], v255 offset:768
	s_nop 0
	ds_read_b128 v[4:7], v255 offset:784
	s_movk_i32 s19, 0x3000
	s_mov_b64 s[42:43], 0x3000
	v_lshl_add_u64 v[32:33], v[14:15], 0, s[42:43]
	s_mov_b64 s[42:43], 0x4800
	v_lshl_add_u64 v[200:201], v[14:15], 0, s[42:43]
	v_pk_mul_f32 v[20:21], v[26:27], v[20:21] op_sel_hi:[0,1]
	s_mov_b64 s[42:43], 0x2000
	s_waitcnt lgkmcnt(0)
	v_pk_mul_f32 v[28:29], v[24:25], v[28:29] op_sel_hi:[0,1]
	s_waitcnt lgkmcnt(0)
	v_pk_mul_f32 v[12:13], v[6:7], v[24:25] op_sel_hi:[1,0]
	v_add_co_u32_e32 v6, vcc, s19, v14
	s_movk_i32 s19, 0x4000
	s_nop 0
	v_addc_co_u32_e32 v7, vcc, 0, v15, vcc
	v_pk_mul_f32 v[16:17], v[4:5], v[24:25] op_sel_hi:[1,0]
	v_add_co_u32_e32 v4, vcc, s19, v14
	v_pk_mul_f32 v[30:31], v[24:25], v[30:31] op_sel_hi:[0,1]
	s_nop 0
	v_addc_co_u32_e32 v5, vcc, 0, v15, vcc
	ds_read_b128 v[94:97], v255 offset:1536
	ds_read_b128 v[196:199], v255 offset:1552
	s_movk_i32 s19, 0x2000
	s_waitcnt lgkmcnt(0)
	v_pk_mul_f32 v[94:95], v[22:23], v[94:95] op_sel_hi:[0,1]
	s_waitcnt lgkmcnt(0)
	v_pk_mul_f32 v[32:33], v[198:199], v[22:23] op_sel_hi:[1,0]
	v_pk_mul_f32 v[98:99], v[196:197], v[22:23] op_sel_hi:[1,0]
	ds_read_b128 v[196:199], v255 offset:2304
	ds_read_b128 v[204:207], v255 offset:2320
	v_lshlrev_b32_e32 v200, 16, v70
	v_and_b32_e32 v201, 0xffff0000, v70
	v_pk_fma_f32 v[18:19], v[18:19], v[200:201], 0 op_sel_hi:[1,1,0]
	v_lshlrev_b32_e32 v200, 16, v74
	v_and_b32_e32 v201, 0xffff0000, v74
	v_pk_fma_f32 v[18:19], v[28:29], v[200:201], v[18:19]
	v_lshlrev_b32_e32 v28, 16, v58
	v_and_b32_e32 v29, 0xffff0000, v58
	v_pk_fma_f32 v[18:19], v[94:95], v[28:29], v[18:19]
	v_lshlrev_b32_e32 v28, 16, v78
	v_and_b32_e32 v29, 0xffff0000, v78
	v_pk_mul_f32 v[96:97], v[22:23], v[96:97] op_sel_hi:[0,1]
	s_waitcnt lgkmcnt(0)
	v_pk_fma_f32 v[18:19], v[196:197], v[28:29], v[18:19]
	s_nop 0
	v_mul_f32_e32 v23, 0xbfb8aa3b, v18
	v_exp_f32_e32 v23, v23
	s_nop 0
	v_add_f32_e32 v23, 1.0, v23
	v_rcp_f32_e32 v28, v23
	v_mul_f32_e32 v23, 0xbfb8aa3b, v19
	v_exp_f32_e32 v23, v23
	s_nop 0
	v_add_f32_e32 v23, 1.0, v23
	v_rcp_f32_e32 v29, v23
	s_nop 0
	v_pk_mul_f32 v[28:29], v[18:19], v[28:29]
	v_lshlrev_b32_e32 v18, 16, v71
	v_and_b32_e32 v19, 0xffff0000, v71
	v_pk_fma_f32 v[18:19], v[20:21], v[18:19], 0 op_sel_hi:[1,1,0]
	v_lshlrev_b32_e32 v20, 16, v75
	v_and_b32_e32 v21, 0xffff0000, v75
	v_pk_fma_f32 v[18:19], v[30:31], v[20:21], v[18:19]
	v_lshlrev_b32_e32 v20, 16, v59
	v_and_b32_e32 v21, 0xffff0000, v59
	v_pk_fma_f32 v[18:19], v[96:97], v[20:21], v[18:19]
	v_lshlrev_b32_e32 v20, 16, v79
	v_and_b32_e32 v21, 0xffff0000, v79
	v_pk_fma_f32 v[18:19], v[198:199], v[20:21], v[18:19]
	s_nop 0
	v_mul_f32_e32 v20, 0xbfb8aa3b, v18
	v_mul_f32_e32 v21, 0xbfb8aa3b, v19
	v_exp_f32_e32 v20, v20
	v_exp_f32_e32 v21, v21
	v_add_f32_e32 v20, 1.0, v20
	v_add_f32_e32 v21, 1.0, v21
	v_rcp_f32_e32 v20, v20
	v_rcp_f32_e32 v21, v21
	s_nop 0
	v_pk_mul_f32 v[20:21], v[18:19], v[20:21]
	v_lshlrev_b32_e32 v18, 16, v72
	v_and_b32_e32 v19, 0xffff0000, v72
	v_pk_fma_f32 v[10:11], v[10:11], v[18:19], 0 op_sel_hi:[1,1,0]
	v_lshlrev_b32_e32 v18, 16, v76
	v_and_b32_e32 v19, 0xffff0000, v76
	v_pk_fma_f32 v[10:11], v[16:17], v[18:19], v[10:11]
	v_lshlrev_b32_e32 v16, 16, v60
	v_and_b32_e32 v17, 0xffff0000, v60
	v_pk_fma_f32 v[10:11], v[98:99], v[16:17], v[10:11]
	v_lshlrev_b32_e32 v16, 16, v80
	v_and_b32_e32 v17, 0xffff0000, v80
	s_waitcnt lgkmcnt(0)
	v_pk_fma_f32 v[10:11], v[204:205], v[16:17], v[10:11]
	v_add_co_u32_e32 v98, vcc, s19, v14
	v_mul_f32_e32 v16, 0xbfb8aa3b, v10
	v_mul_f32_e32 v17, 0xbfb8aa3b, v11
	v_exp_f32_e32 v16, v16
	v_exp_f32_e32 v17, v17
	v_addc_co_u32_e32 v99, vcc, 0, v15, vcc
	v_add_f32_e32 v16, 1.0, v16
	v_add_f32_e32 v17, 1.0, v17
	v_rcp_f32_e32 v16, v16
	v_rcp_f32_e32 v17, v17
	s_movk_i32 s19, 0x5000
	v_pk_mul_f32 v[30:31], v[10:11], v[16:17]
	v_lshlrev_b32_e32 v10, 16, v73
	v_and_b32_e32 v11, 0xffff0000, v73
	v_pk_fma_f32 v[8:9], v[8:9], v[10:11], 0 op_sel_hi:[1,1,0]
	v_lshlrev_b32_e32 v10, 16, v77
	v_and_b32_e32 v11, 0xffff0000, v77
	v_pk_fma_f32 v[8:9], v[12:13], v[10:11], v[8:9]
	v_lshlrev_b32_e32 v10, 16, v61
	v_and_b32_e32 v11, 0xffff0000, v61
	v_pk_fma_f32 v[8:9], v[32:33], v[10:11], v[8:9]
	v_lshlrev_b32_e32 v10, 16, v81
	v_and_b32_e32 v11, 0xffff0000, v81
	v_pk_fma_f32 v[8:9], v[206:207], v[10:11], v[8:9]
	v_mov_b32_e32 v17, v31
	v_mul_f32_e32 v10, 0xbfb8aa3b, v9
	v_exp_f32_e32 v10, v10
	s_nop 0
	v_add_f32_e32 v10, 1.0, v10
	v_rcp_f32_e32 v11, v10
	v_mul_f32_e32 v10, 0xbfb8aa3b, v8
	v_exp_f32_e32 v10, v10
	s_nop 0
	v_add_f32_e32 v10, 1.0, v10
	v_rcp_f32_e32 v10, v10
	s_nop 0
	v_pk_mul_f32 v[12:13], v[8:9], v[10:11]
	v_mov_b32_e32 v10, v29
	v_mov_b32_e32 v11, v21
	v_mov_b32_e32 v8, v28
	v_mov_b32_e32 v9, v20
	v_pk_mul_f32 v[10:11], v[10:11], v[10:11]
	v_mov_b32_e32 v16, v13
	v_pk_fma_f32 v[8:9], v[8:9], v[8:9], v[10:11]
	v_mov_b32_e32 v10, v12
	v_mov_b32_e32 v11, v30
	v_pk_mul_f32 v[16:17], v[16:17], v[16:17]
	v_add_f32_e32 v8, v8, v9
	v_pk_fma_f32 v[10:11], v[10:11], v[10:11], v[16:17]
	s_nop 0
	v_add_f32_e32 v8, v11, v8
	v_add_f32_e32 v8, v10, v8
	ds_bpermute_b32 v9, v101, v8
	s_waitcnt lgkmcnt(0)
; #define LAS __attribute__((address_space(3)))
; DI unsigned pk2(float lo, float hi) { typedef __bf16 b2 __attribute__((ext_vector_type(2))); f32x2 v = {lo, hi}; b2 b = __builtin_convertvector(v, b2); return __builtin_bit_cast(unsigned, b); }
; DI float bflo(unsigned w) { return __uint_as_float(w << 16); }
; DI float bfhi(unsigned w) { return __uint_as_float(w & 0xffff0000u); }
;     ...
;         for (int j = 0; j < 4; ++j) { const int sp = n * 64 + t - 3 + j; const float ok = sp >= 0 ? 1.f : 0.f;
;             const u32x4 xv = xin[which * 4 + j];
;             const f32x4 w0 = *(const f32x4*)(conv_w + j * 1536 + col) * ok, w1 = *(const f32x4*)(conv_w + j * 1536 + col + 4) * ok;
;             acc[0] += w0[0] * bflo(xv.x); acc[1] += w0[1] * bfhi(xv.x); acc[2] += w0[2] * bflo(xv.y); acc[3] += w0[3] * bfhi(xv.y);
;             acc[4] += w1[0] * bflo(xv.z); acc[5] += w1[1] * bfhi(xv.z); acc[6] += w1[2] * bflo(xv.w); acc[7] += w1[3] * bfhi(xv.w); }
; #pragma unroll
;         for (int e = 0; e < 8; ++e) acc[e] = silu_f(acc[e]);
;         if (which == 2) { LAS float* dst = vc + t * 68 + cg8 * 8; *(LAS f32x4*)dst = (f32x4){acc[0], acc[1], acc[2], acc[3]}; *(LAS f32x4*)(dst + 4) = (f32x4){acc[4], acc[5], acc[6], acc[7]}; }
;         else {
;             float ss = (acc[0] * acc[0] + acc[1] * acc[1]) + (acc[2] * acc[2] + acc[3] * acc[3]) + (acc[4] * acc[4] + acc[5] * acc[5]) + (acc[6] * acc[6] + acc[7] * acc[7]);
;             ss += __shfl_xor(ss, 1); ss += __shfl_xor(ss, 2); ss += __shfl_xor(ss, 4);
;             const float sc = (which ? 1.0f : 0.125f) * __builtin_amdgcn_rsqf(ss + 1e-6f);
;             const f32x4 y0 = (f32x4){acc[0], acc[1], acc[2], acc[3]} * sc, y1 = (f32x4){acc[4], acc[5], acc[6], acc[7]} * sc;
;             LAS float* dst = (which ? kc : qc) + t * 68 + cg8 * 8; *(LAS f32x4*)dst = y0; *(LAS f32x4*)(dst + 4) = y1;
;             u32x4 hh; hh.x = pk2(y0[0], y0[1]); hh.y = pk2(y0[2], y0[3]); hh.z = pk2(y1[0], y1[1]); hh.w = pk2(y1[2], y1[3]);
;             u32x4 lo; lo.x = pk2(y0[0] - bflo(hh.x), y0[1] - bfhi(hh.x)); lo.y = pk2(y0[2] - bflo(hh.y), y0[3] - bfhi(hh.y)); lo.z = pk2(y1[0] - bflo(hh.z), y1[1] - bfhi(hh.z)); lo.w = pk2(y1[2] - bflo(hh.w), y1[3] - bfhi(hh.w));
;             *(LAS u32x4*)((which ? KH : QH) + t * 72 + cg8 * 8) = hh; *(LAS u32x4*)((which ? KL : QL) + t * 72 + cg8 * 8) = lo; }
	v_add_f32_e32 v8, v8, v9
	ds_bpermute_b32 v9, v102, v8
	s_waitcnt lgkmcnt(0)
	v_add_f32_e32 v8, v8, v9
	ds_bpermute_b32 v9, v103, v8
	s_waitcnt lgkmcnt(0)
	v_add_f32_e32 v8, v8, v9
	v_add_f32_e32 v8, 0x358637bd, v8
	v_rsq_f32_e32 v8, v8
	s_nop 0
	v_mul_f32_e32 v32, 0x3e000000, v8
	v_pk_mul_f32 v[10:11], v[20:21], v[32:33] op_sel_hi:[1,0]
	v_pk_mul_f32 v[8:9], v[28:29], v[32:33] op_sel_hi:[1,0]
	v_pk_mul_f32 v[18:19], v[12:13], v[32:33] op_sel_hi:[1,0]
	v_pk_mul_f32 v[16:17], v[30:31], v[32:33] op_sel_hi:[1,0]
	ds_write_b128 v112, v[8:11]
	ds_write_b128 v112, v[16:19] offset:16
	v_cvt_pk_bf16_f32 v8, v8, v9
	v_cvt_pk_bf16_f32 v9, v10, v11
	v_cvt_pk_bf16_f32 v10, v16, v17
	v_cvt_pk_bf16_f32 v11, v18, v19
	v_lshlrev_b32_e32 v16, 16, v8
	v_and_b32_e32 v17, 0xffff0000, v8
	v_lshlrev_b32_e32 v18, 16, v9
	v_and_b32_e32 v19, 0xffff0000, v9
	v_pk_fma_f32 v[16:17], v[28:29], v[32:33], v[16:17] op_sel_hi:[1,0,1] neg_lo:[0,0,1] neg_hi:[0,0,1]
	v_pk_fma_f32 v[18:19], v[20:21], v[32:33], v[18:19] op_sel_hi:[1,0,1] neg_lo:[0,0,1] neg_hi:[0,0,1]
	v_cvt_pk_bf16_f32 v16, v16, v17
	v_cvt_pk_bf16_f32 v17, v18, v19
	v_lshlrev_b32_e32 v18, 16, v10
	v_and_b32_e32 v19, 0xffff0000, v10
	v_lshlrev_b32_e32 v20, 16, v11
	v_and_b32_e32 v21, 0xffff0000, v11
	v_pk_fma_f32 v[18:19], v[30:31], v[32:33], v[18:19] op_sel_hi:[1,0,1] neg_lo:[0,0,1] neg_hi:[0,0,1]
	v_pk_fma_f32 v[12:13], v[12:13], v[32:33], v[20:21] op_sel_hi:[1,0,1] neg_lo:[0,0,1] neg_hi:[0,0,1]
	v_cvt_pk_bf16_f32 v18, v18, v19
	v_cvt_pk_bf16_f32 v19, v12, v13
	ds_write_b128 v113, v[8:11]
	ds_write_b128 v114, v[16:19]
	ds_read_b128 v[8:11], v255 offset:256
	ds_read_b128 v[16:19], v255 offset:272
	s_waitcnt lgkmcnt(0)
	v_pk_mul_f32 v[8:9], v[26:27], v[8:9] op_sel_hi:[0,1]
	s_waitcnt lgkmcnt(0)
	v_pk_mul_f32 v[12:13], v[26:27], v[18:19] op_sel_hi:[0,1]
	v_pk_mul_f32 v[32:33], v[26:27], v[16:17] op_sel_hi:[0,1]
	v_lshl_add_u64 v[16:17], v[14:15], 0, s[42:43]
	ds_read_b128 v[18:21], v255 offset:1024
	ds_read_b128 v[28:31], v255 offset:1040
	s_mov_b64 s[42:43], 0x3800
	v_lshl_add_u64 v[16:17], v[14:15], 0, s[42:43]
	s_mov_b64 s[42:43], 0x5000
	v_lshl_add_u64 v[196:197], v[14:15], 0, s[42:43]
	v_pk_fma_f32 v[8:9], v[8:9], v[208:209], 0 op_sel_hi:[1,1,0]
	v_lshlrev_b32_e32 v208, 16, v62
	v_and_b32_e32 v209, 0xffff0000, v62
	v_pk_mul_f32 v[10:11], v[26:27], v[10:11] op_sel_hi:[0,1]
	s_mov_b64 s[42:43], 0x1000
	s_waitcnt lgkmcnt(0)
	v_pk_mul_f32 v[18:19], v[24:25], v[18:19] op_sel_hi:[0,1]
	s_waitcnt lgkmcnt(0)
	v_pk_mul_f32 v[200:201], v[24:25], v[30:31] op_sel_hi:[0,1]
	v_pk_mul_f32 v[204:205], v[24:25], v[28:29] op_sel_hi:[0,1]
	ds_read_b128 v[28:31], v255 offset:1792
	ds_read_b128 v[94:97], v255 offset:1808
	v_add_co_u32_e32 v16, vcc, s19, v14
	v_pk_fma_f32 v[8:9], v[18:19], v[208:209], v[8:9]
	s_nop 0
	v_addc_co_u32_e32 v17, vcc, 0, v15, vcc
	v_lshlrev_b32_e32 v18, 16, v50
	v_and_b32_e32 v19, 0xffff0000, v50
	v_pk_mul_f32 v[20:21], v[24:25], v[20:21] op_sel_hi:[0,1]
	s_andn2_b64 vcc, exec, s[20:21]
	s_waitcnt lgkmcnt(0)
	v_pk_mul_f32 v[28:29], v[22:23], v[28:29] op_sel_hi:[0,1]
	s_waitcnt lgkmcnt(0)
	v_pk_mul_f32 v[6:7], v[22:23], v[96:97] op_sel_hi:[0,1]
	v_pk_mul_f32 v[206:207], v[22:23], v[94:95] op_sel_hi:[0,1]
	ds_read_b128 v[94:97], v255 offset:2560
	s_nop 0
	ds_read_b128 v[196:199], v255 offset:2576
	v_pk_fma_f32 v[8:9], v[28:29], v[18:19], v[8:9]
	v_lshlrev_b32_e32 v18, 16, v66
	v_and_b32_e32 v19, 0xffff0000, v66
	v_pk_mul_f32 v[30:31], v[22:23], v[30:31] op_sel_hi:[0,1]
	s_waitcnt lgkmcnt(0)
	v_pk_fma_f32 v[8:9], v[94:95], v[18:19], v[8:9]
	s_nop 0
	v_mul_f32_e32 v18, 0xbfb8aa3b, v8
	v_mul_f32_e32 v19, 0xbfb8aa3b, v9
	v_exp_f32_e32 v18, v18
	v_exp_f32_e32 v19, v19
	v_add_f32_e32 v18, 1.0, v18
	v_add_f32_e32 v19, 1.0, v19
	v_rcp_f32_e32 v18, v18
	v_rcp_f32_e32 v19, v19
	s_nop 0
	v_pk_mul_f32 v[18:19], v[8:9], v[18:19]
	v_lshlrev_b32_e32 v8, 16, v55
	v_and_b32_e32 v9, 0xffff0000, v55
	v_pk_fma_f32 v[8:9], v[10:11], v[8:9], 0 op_sel_hi:[1,1,0]
	v_lshlrev_b32_e32 v10, 16, v63
	v_and_b32_e32 v11, 0xffff0000, v63
	v_pk_fma_f32 v[8:9], v[20:21], v[10:11], v[8:9]
	v_lshlrev_b32_e32 v10, 16, v51
	v_and_b32_e32 v11, 0xffff0000, v51
	v_pk_fma_f32 v[8:9], v[30:31], v[10:11], v[8:9]
	v_lshlrev_b32_e32 v10, 16, v67
	v_and_b32_e32 v11, 0xffff0000, v67
	v_pk_fma_f32 v[8:9], v[96:97], v[10:11], v[8:9]
	s_nop 0
	v_mul_f32_e32 v10, 0xbfb8aa3b, v8
	v_mul_f32_e32 v11, 0xbfb8aa3b, v9
	v_exp_f32_e32 v10, v10
	v_exp_f32_e32 v11, v11
	v_add_f32_e32 v10, 1.0, v10
	v_add_f32_e32 v11, 1.0, v11
	v_rcp_f32_e32 v10, v10
	v_rcp_f32_e32 v11, v11
	s_nop 0
	v_pk_mul_f32 v[20:21], v[8:9], v[10:11]
	v_lshlrev_b32_e32 v8, 16, v56
	v_and_b32_e32 v9, 0xffff0000, v56
	v_pk_fma_f32 v[8:9], v[32:33], v[8:9], 0 op_sel_hi:[1,1,0]
	v_lshlrev_b32_e32 v10, 16, v64
	v_and_b32_e32 v11, 0xffff0000, v64
	v_pk_fma_f32 v[8:9], v[204:205], v[10:11], v[8:9]
	v_lshlrev_b32_e32 v10, 16, v52
	v_and_b32_e32 v11, 0xffff0000, v52
	v_pk_fma_f32 v[8:9], v[206:207], v[10:11], v[8:9]
	v_lshlrev_b32_e32 v10, 16, v68
	v_and_b32_e32 v11, 0xffff0000, v68
	s_waitcnt lgkmcnt(0)
; #define LAS __attribute__((address_space(3)))
; DI float bflo(unsigned w) { return __uint_as_float(w << 16); }
; DI float bfhi(unsigned w) { return __uint_as_float(w & 0xffff0000u); }
;     ...
;     for (int which = 0; which < 3; ++which) {
;         const int t = tid >> 3, cg8 = tid & 7; const int col = which * 512 + h * 64 + cg8 * 8;
;         float acc[8];
; #pragma unroll
;         for (int e = 0; e < 8; ++e) acc[e] = 0.f;
; #pragma unroll
;         for (int j = 0; j < 4; ++j) { const int sp = n * 64 + t - 3 + j; const float ok = sp >= 0 ? 1.f : 0.f;
;             const u32x4 xv = xin[which * 4 + j];
;             const f32x4 w0 = *(const f32x4*)(conv_w + j * 1536 + col) * ok, w1 = *(const f32x4*)(conv_w + j * 1536 + col + 4) * ok;
;             acc[0] += w0[0] * bflo(xv.x); acc[1] += w0[1] * bfhi(xv.x); acc[2] += w0[2] * bflo(xv.y); acc[3] += w0[3] * bfhi(xv.y);
;             acc[4] += w1[0] * bflo(xv.z); acc[5] += w1[1] * bfhi(xv.z); acc[6] += w1[2] * bflo(xv.w); acc[7] += w1[3] * bfhi(xv.w); }
; #pragma unroll
;         for (int e = 0; e < 8; ++e) acc[e] = silu_f(acc[e]);
;         if (which == 2) { LAS float* dst = vc + t * 68 + cg8 * 8; *(LAS f32x4*)dst = (f32x4){acc[0], acc[1], acc[2], acc[3]}; *(LAS f32x4*)(dst + 4) = (f32x4){acc[4], acc[5], acc[6], acc[7]}; }
;         else {
;             float ss = (acc[0] * acc[0] + acc[1] * acc[1]) + (acc[2] * acc[2] + acc[3] * acc[3]) + (acc[4] * acc[4] + acc[5] * acc[5]) + (acc[6] * acc[6] + acc[7] * acc[7]);
;             ss += __shfl_xor(ss, 1); ss += __shfl_xor(ss, 2); ss += __shfl_xor(ss, 4);
;             const float sc = (which ? 1.0f : 0.125f) * __builtin_amdgcn_rsqf(ss + 1e-6f);
;             const f32x4 y0 = (f32x4){acc[0], acc[1], acc[2], acc[3]} * sc, y1 = (f32x4){acc[4], acc[5], acc[6], acc[7]} * sc;
;             LAS float* dst = (which ? kc : qc) + t * 68 + cg8 * 8; *(LAS f32x4*)dst = y0; *(LAS f32x4*)(dst + 4) = y1;
;             u32x4 hh; hh.x = pk2(y0[0], y0[1]); hh.y = pk2(y0[2], y0[3]); hh.z = pk2(y1[0], y1[1]); hh.w = pk2(y1[2], y1[3]);
;             u32x4 lo; lo.x = pk2(y0[0] - bflo(hh.x), y0[1] - bfhi(hh.x)); lo.y = pk2(y0[2] - bflo(hh.y), y0[3] - bfhi(hh.y)); lo.z = pk2(y1[0] - bflo(hh.z), y1[1] - bfhi(hh.z)); lo.w = pk2(y1[2] - bflo(hh.w), y1[3] - bfhi(hh.w));
;             *(LAS u32x4*)((which ? KH : QH) + t * 72 + cg8 * 8) = hh; *(LAS u32x4*)((which ? KL : QL) + t * 72 + cg8 * 8) = lo; }
	v_pk_fma_f32 v[8:9], v[196:197], v[10:11], v[8:9]
	s_nop 0
	v_mul_f32_e32 v10, 0xbfb8aa3b, v8
	v_mul_f32_e32 v11, 0xbfb8aa3b, v9
	v_exp_f32_e32 v10, v10
	v_exp_f32_e32 v11, v11
	v_add_f32_e32 v10, 1.0, v10
	v_add_f32_e32 v11, 1.0, v11
	v_rcp_f32_e32 v10, v10
	v_rcp_f32_e32 v11, v11
	s_nop 0
	v_pk_mul_f32 v[28:29], v[8:9], v[10:11]
	v_lshlrev_b32_e32 v8, 16, v57
	v_and_b32_e32 v9, 0xffff0000, v57
	v_pk_fma_f32 v[8:9], v[12:13], v[8:9], 0 op_sel_hi:[1,1,0]
	v_lshlrev_b32_e32 v10, 16, v65
	v_and_b32_e32 v11, 0xffff0000, v65
	v_pk_fma_f32 v[8:9], v[200:201], v[10:11], v[8:9]
	v_lshlrev_b32_e32 v10, 16, v53
	v_and_b32_e32 v11, 0xffff0000, v53
	v_pk_fma_f32 v[6:7], v[6:7], v[10:11], v[8:9]
	v_lshlrev_b32_e32 v8, 16, v69
	v_and_b32_e32 v9, 0xffff0000, v69
	v_pk_fma_f32 v[6:7], v[198:199], v[8:9], v[6:7]
	v_mov_b32_e32 v11, v29
	v_mul_f32_e32 v8, 0xbfb8aa3b, v7
	v_exp_f32_e32 v8, v8
	s_nop 0
	v_add_f32_e32 v8, 1.0, v8
	v_rcp_f32_e32 v9, v8
	v_mul_f32_e32 v8, 0xbfb8aa3b, v6
	v_exp_f32_e32 v8, v8
	s_nop 0
	v_add_f32_e32 v8, 1.0, v8
	v_rcp_f32_e32 v8, v8
	s_nop 0
	v_pk_mul_f32 v[30:31], v[6:7], v[8:9]
	v_mov_b32_e32 v8, v19
	v_mov_b32_e32 v9, v21
	v_mov_b32_e32 v6, v18
	v_mov_b32_e32 v7, v20
	v_pk_mul_f32 v[8:9], v[8:9], v[8:9]
	v_mov_b32_e32 v10, v31
	v_pk_fma_f32 v[6:7], v[6:7], v[6:7], v[8:9]
	v_mov_b32_e32 v8, v30
	v_mov_b32_e32 v9, v28
	v_pk_mul_f32 v[10:11], v[10:11], v[10:11]
	v_add_f32_e32 v6, v6, v7
	v_pk_fma_f32 v[8:9], v[8:9], v[8:9], v[10:11]
	s_nop 0
	v_add_f32_e32 v6, v9, v6
	v_add_f32_e32 v6, v8, v6
	ds_bpermute_b32 v7, v101, v6
	s_waitcnt lgkmcnt(0)
	v_add_f32_e32 v6, v6, v7
	ds_bpermute_b32 v7, v102, v6
	s_waitcnt lgkmcnt(0)
	v_add_f32_e32 v6, v6, v7
	ds_bpermute_b32 v7, v103, v6
	s_waitcnt lgkmcnt(0)
	v_add_f32_e32 v6, v6, v7
	v_add_f32_e32 v6, 0x358637bd, v6
	v_rsq_f32_e32 v32, v6
	s_nop 0
	v_pk_mul_f32 v[8:9], v[20:21], v[32:33] op_sel_hi:[1,0]
	v_pk_mul_f32 v[6:7], v[18:19], v[32:33] op_sel_hi:[1,0]
	v_pk_mul_f32 v[12:13], v[30:31], v[32:33] op_sel_hi:[1,0]
	v_pk_mul_f32 v[10:11], v[28:29], v[32:33] op_sel_hi:[1,0]
	ds_write_b128 v112, v[6:9] offset:17408
	ds_write_b128 v112, v[10:13] offset:17424
	v_cvt_pk_bf16_f32 v6, v6, v7
	v_cvt_pk_bf16_f32 v7, v8, v9
	v_cvt_pk_bf16_f32 v8, v10, v11
	v_cvt_pk_bf16_f32 v9, v12, v13
	v_lshlrev_b32_e32 v10, 16, v6
	v_and_b32_e32 v11, 0xffff0000, v6
	v_lshlrev_b32_e32 v12, 16, v7
	v_and_b32_e32 v13, 0xffff0000, v7
	v_pk_fma_f32 v[10:11], v[18:19], v[32:33], v[10:11] op_sel_hi:[1,0,1] neg_lo:[0,0,1] neg_hi:[0,0,1]
	v_pk_fma_f32 v[12:13], v[20:21], v[32:33], v[12:13] op_sel_hi:[1,0,1] neg_lo:[0,0,1] neg_hi:[0,0,1]
	v_cvt_pk_bf16_f32 v10, v10, v11
	v_cvt_pk_bf16_f32 v11, v12, v13
	v_lshlrev_b32_e32 v12, 16, v8
	v_and_b32_e32 v13, 0xffff0000, v8
	v_lshlrev_b32_e32 v18, 16, v9
	v_and_b32_e32 v19, 0xffff0000, v9
	v_pk_fma_f32 v[12:13], v[28:29], v[32:33], v[12:13] op_sel_hi:[1,0,1] neg_lo:[0,0,1] neg_hi:[0,0,1]
	v_pk_fma_f32 v[18:19], v[30:31], v[32:33], v[18:19] op_sel_hi:[1,0,1] neg_lo:[0,0,1] neg_hi:[0,0,1]
	v_cvt_pk_bf16_f32 v12, v12, v13
	v_cvt_pk_bf16_f32 v13, v18, v19
	ds_write_b128 v115, v[6:9]
	ds_write_b128 v116, v[10:13]
	v_lshl_add_u64 v[10:11], v[14:15], 0, s[42:43]
	ds_read_b128 v[6:9], v255 offset:512
	s_nop 0
	ds_read_b128 v[10:13], v255 offset:528
	s_mov_b64 s[42:43], 0x2800
	v_lshl_add_u64 v[2:3], v[14:15], 0, s[42:43]
	s_mov_b64 s[42:43], 0x5800
	s_waitcnt lgkmcnt(0)
	v_pk_mul_f32 v[6:7], v[26:27], v[6:7] op_sel_hi:[0,1]
	s_waitcnt lgkmcnt(0)
	v_pk_mul_f32 v[28:29], v[26:27], v[12:13] op_sel_hi:[0,1]
	v_pk_mul_f32 v[94:95], v[26:27], v[10:11] op_sel_hi:[0,1]
	ds_read_b128 v[10:13], v255 offset:1280
	ds_read_b128 v[18:21], v255 offset:1296
	v_pk_mul_f32 v[8:9], v[26:27], v[8:9] op_sel_hi:[0,1]
	s_waitcnt lgkmcnt(0)
	v_pk_mul_f32 v[10:11], v[24:25], v[10:11] op_sel_hi:[0,1]
	s_waitcnt lgkmcnt(0)
	v_pk_mul_f32 v[96:97], v[24:25], v[18:19] op_sel_hi:[0,1]
	v_lshl_add_u64 v[18:19], v[14:15], 0, s[28:29]
	v_pk_mul_f32 v[30:31], v[24:25], v[20:21] op_sel_hi:[0,1]
	ds_read_b128 v[2:5], v255 offset:2048
	s_nop 0
	ds_read_b128 v[18:21], v255 offset:2064
	v_pk_mul_f32 v[12:13], v[24:25], v[12:13] op_sel_hi:[0,1]
	s_waitcnt lgkmcnt(0)
	v_pk_mul_f32 v[4:5], v[22:23], v[4:5] op_sel_hi:[0,1]
	s_waitcnt lgkmcnt(0)
	v_pk_mul_f32 v[98:99], v[22:23], v[18:19] op_sel_hi:[0,1]
	v_lshl_add_u64 v[18:19], v[14:15], 0, s[42:43]
	v_pk_mul_f32 v[32:33], v[22:23], v[20:21] op_sel_hi:[0,1]
	ds_read_b128 v[14:17], v255 offset:2816
	s_nop 0
	ds_read_b128 v[18:21], v255 offset:2832
	v_pk_mul_f32 v[2:3], v[22:23], v[2:3] op_sel_hi:[0,1]
	v_lshlrev_b32_e32 v22, 16, v34
	v_and_b32_e32 v23, 0xffff0000, v34
	v_pk_fma_f32 v[6:7], v[6:7], v[22:23], 0 op_sel_hi:[1,1,0]
	v_lshlrev_b32_e32 v22, 16, v38
	v_and_b32_e32 v23, 0xffff0000, v38
	v_pk_fma_f32 v[6:7], v[10:11], v[22:23], v[6:7]
	v_lshlrev_b32_e32 v10, 16, v42
	v_and_b32_e32 v11, 0xffff0000, v42
	v_pk_fma_f32 v[2:3], v[2:3], v[10:11], v[6:7]
	v_lshlrev_b32_e32 v10, 16, v35
	v_and_b32_e32 v11, 0xffff0000, v35
	v_pk_fma_f32 v[8:9], v[8:9], v[10:11], 0 op_sel_hi:[1,1,0]
	v_lshlrev_b32_e32 v10, 16, v39
	v_and_b32_e32 v11, 0xffff0000, v39
	v_lshlrev_b32_e32 v6, 16, v46
	v_and_b32_e32 v7, 0xffff0000, v46
	v_pk_fma_f32 v[8:9], v[12:13], v[10:11], v[8:9]
	v_lshlrev_b32_e32 v10, 16, v43
	v_and_b32_e32 v11, 0xffff0000, v43
	v_pk_fma_f32 v[4:5], v[4:5], v[10:11], v[8:9]
	v_lshlrev_b32_e32 v8, 16, v47
	v_and_b32_e32 v9, 0xffff0000, v47
	v_lshlrev_b32_e32 v10, 16, v37
	v_and_b32_e32 v11, 0xffff0000, v37
	v_pk_fma_f32 v[10:11], v[28:29], v[10:11], 0 op_sel_hi:[1,1,0]
	v_lshlrev_b32_e32 v12, 16, v41
	v_and_b32_e32 v13, 0xffff0000, v41
	v_pk_fma_f32 v[10:11], v[30:31], v[12:13], v[10:11]
	v_lshlrev_b32_e32 v12, 16, v45
	v_and_b32_e32 v13, 0xffff0000, v45
	v_pk_fma_f32 v[10:11], v[32:33], v[12:13], v[10:11]
	v_lshlrev_b32_e32 v12, 16, v49
	v_and_b32_e32 v13, 0xffff0000, v49
	s_waitcnt lgkmcnt(0)
; #define LAS __attribute__((address_space(3)))
; DI float bflo(unsigned w) { return __uint_as_float(w << 16); }
; DI float bfhi(unsigned w) { return __uint_as_float(w & 0xffff0000u); }
; DI float silu_f(float g) { return g * frcp(1.f + fexp2(-1.4426950408889634f * g)); }
;     ...
;         for (int j = 0; j < 4; ++j) { const int sp = n * 64 + t - 3 + j; const float ok = sp >= 0 ? 1.f : 0.f;
;             const u32x4 xv = xin[which * 4 + j];
;             const f32x4 w0 = *(const f32x4*)(conv_w + j * 1536 + col) * ok, w1 = *(const f32x4*)(conv_w + j * 1536 + col + 4) * ok;
;             acc[0] += w0[0] * bflo(xv.x); acc[1] += w0[1] * bfhi(xv.x); acc[2] += w0[2] * bflo(xv.y); acc[3] += w0[3] * bfhi(xv.y);
;             acc[4] += w1[0] * bflo(xv.z); acc[5] += w1[1] * bfhi(xv.z); acc[6] += w1[2] * bflo(xv.w); acc[7] += w1[3] * bfhi(xv.w); }
; #pragma unroll
;         for (int e = 0; e < 8; ++e) acc[e] = silu_f(acc[e]);
;         if (which == 2) { LAS float* dst = vc + t * 68 + cg8 * 8; *(LAS f32x4*)dst = (f32x4){acc[0], acc[1], acc[2], acc[3]}; *(LAS f32x4*)(dst + 4) = (f32x4){acc[4], acc[5], acc[6], acc[7]}; }
	v_pk_fma_f32 v[2:3], v[14:15], v[6:7], v[2:3]
	s_nop 0
	v_mul_f32_e32 v6, 0xbfb8aa3b, v2
	v_mul_f32_e32 v7, 0xbfb8aa3b, v3
	v_pk_fma_f32 v[4:5], v[16:17], v[8:9], v[4:5]
	v_exp_f32_e32 v6, v6
	v_exp_f32_e32 v7, v7
	v_mul_f32_e32 v8, 0xbfb8aa3b, v4
	v_mul_f32_e32 v9, 0xbfb8aa3b, v5
	v_exp_f32_e32 v8, v8
	v_exp_f32_e32 v9, v9
	v_add_f32_e32 v6, 1.0, v6
	v_add_f32_e32 v7, 1.0, v7
	v_rcp_f32_e32 v6, v6
	v_rcp_f32_e32 v7, v7
	v_add_f32_e32 v8, 1.0, v8
	v_add_f32_e32 v9, 1.0, v9
	v_rcp_f32_e32 v8, v8
	v_rcp_f32_e32 v9, v9
	s_waitcnt lgkmcnt(0)
	v_pk_fma_f32 v[10:11], v[20:21], v[12:13], v[10:11]
	v_pk_mul_f32 v[2:3], v[2:3], v[6:7]
	v_mul_f32_e32 v12, 0xbfb8aa3b, v11
	v_lshlrev_b32_e32 v6, 16, v36
	v_and_b32_e32 v7, 0xffff0000, v36
	v_exp_f32_e32 v12, v12
	v_pk_mul_f32 v[4:5], v[4:5], v[8:9]
	v_pk_fma_f32 v[6:7], v[94:95], v[6:7], 0 op_sel_hi:[1,1,0]
	v_lshlrev_b32_e32 v8, 16, v40
	v_and_b32_e32 v9, 0xffff0000, v40
	v_pk_fma_f32 v[6:7], v[96:97], v[8:9], v[6:7]
	v_lshlrev_b32_e32 v8, 16, v44
	v_and_b32_e32 v9, 0xffff0000, v44
	v_pk_fma_f32 v[6:7], v[98:99], v[8:9], v[6:7]
	v_lshlrev_b32_e32 v8, 16, v48
	v_and_b32_e32 v9, 0xffff0000, v48
	v_pk_fma_f32 v[6:7], v[18:19], v[8:9], v[6:7]
	v_add_f32_e32 v12, 1.0, v12
	v_mul_f32_e32 v8, 0xbfb8aa3b, v6
	v_mul_f32_e32 v9, 0xbfb8aa3b, v7
	v_rcp_f32_e32 v13, v12
	v_mul_f32_e32 v12, 0xbfb8aa3b, v10
	v_exp_f32_e32 v8, v8
	v_exp_f32_e32 v9, v9
	v_exp_f32_e32 v12, v12
	v_add_f32_e32 v8, 1.0, v8
	v_add_f32_e32 v9, 1.0, v9
	v_add_f32_e32 v12, 1.0, v12
	v_rcp_f32_e32 v8, v8
	v_rcp_f32_e32 v9, v9
	v_rcp_f32_e32 v12, v12
	v_pk_mul_f32 v[6:7], v[6:7], v[8:9]
	v_pk_mul_f32 v[8:9], v[10:11], v[12:13]
	ds_write_b128 v176, v[2:5] offset:34816
	ds_write_b128 v176, v[6:9] offset:34832
	s_cbranch_vccnz .LBB0_436
; DI float bf2f(bf16_t u) { return __uint_as_float(((unsigned)u) << 16); }
;     ...
;     { const float ga = bf2f(gain), gb = bf2f(gbin);
;         const float x = ga + dt_bias[h]; const float sp = fmaxf(x, 0.f) + log1pf(expf(-fabsf(x)));
;         float gv = -expf(a_log[h]) * sp; const float bv = 1.f / (1.f + expf(-gb));
;         if (wid == 0) {
; #pragma unroll
;             for (int o = 1; o < 64; o <<= 1) { const float tt = __shfl_up(gv, o); if (lane >= o) gv += tt; }
;             gcs[lane] = gv; bet[lane] = bv; } }
	s_lshl_b32 s3, s3, 2
	v_mov_b32_e32 v2, s3
	v_readlane_b32 s52, v247, 9
	global_load_dword v3, v2, s[50:51]
	v_readlane_b32 s53, v247, 10
	v_lshlrev_b32_e32 v5, 16, v1
	s_mov_b32 s3, 0xb2a5705f
	v_readlane_b32 s54, v247, 11
	v_readlane_b32 s55, v247, 12
	v_readlane_b32 s56, v247, 13
	global_load_dword v4, v2, s[52:53]
	v_lshlrev_b32_e32 v2, 16, v100
	v_mul_f32_e32 v6, 0xbfb8aa3b, v2
	v_rndne_f32_e32 v7, v6
	v_fma_f32 v8, v2, s78, -v6
	v_sub_f32_e32 v6, v6, v7
	v_fmac_f32_e32 v8, 0xb2a5705f, v2
	v_add_f32_e32 v6, v6, v8
	v_cvt_i32_f32_e32 v7, v7
	v_exp_f32_e32 v6, v6
	v_readlane_b32 s57, v247, 14
	v_readlane_b32 s58, v247, 15
	v_readlane_b32 s59, v247, 16
	v_ldexp_f32 v6, v6, v7
	v_readlane_b32 s60, v247, 17
	v_readlane_b32 s61, v247, 18
	v_readlane_b32 s62, v247, 19
	v_readlane_b32 s63, v247, 20
	v_readlane_b32 s64, v247, 21
	v_readlane_b32 s65, v247, 22
	v_readlane_b32 s66, v247, 23
	v_readlane_b32 s67, v247, 24
	s_waitcnt vmcnt(1)
	v_mul_f32_e32 v8, 0x3fb8aa3b, v3
	v_rndne_f32_e32 v9, v8
	v_cmp_ngt_f32_e32 vcc, s95, v3
	s_waitcnt vmcnt(0)
	v_add_f32_e32 v4, v4, v5
	v_fma_f32 v5, v3, s27, -v8
	v_mul_f32_e64 v10, |v4|, s78
	v_fmac_f32_e32 v5, 0x32a5705f, v3
	v_sub_f32_e32 v8, v8, v9
	v_fma_f32 v12, |v4|, s78, -v10
	v_rndne_f32_e32 v13, v10
	v_add_f32_e32 v5, v8, v5
	v_cvt_i32_f32_e32 v9, v9
	v_fma_f32 v8, |v4|, s3, v12
	v_sub_f32_e32 v10, v10, v13
	v_exp_f32_e32 v5, v5
	v_add_f32_e32 v8, v10, v8
	v_cvt_i32_f32_e32 v12, v13
	v_exp_f32_e32 v8, v8
	v_ldexp_f32 v5, v5, v9
	v_cndmask_b32_e32 v5, 0, v5, vcc
	v_cmp_nlt_f32_e32 vcc, s16, v3
	v_ldexp_f32 v8, v8, v12
	v_max_f32_e32 v11, 0, v4
	v_cndmask_b32_e32 v3, v193, v5, vcc
	v_cmp_ngt_f32_e64 vcc, |v4|, s79
	s_mov_b32 s3, 0x3f2aaaab
	s_nop 0
	v_cndmask_b32_e32 v5, 0, v8, vcc
	v_cmp_nlt_f32_e64 vcc, |v4|, s26
	s_nop 1
	v_cndmask_b32_e32 v8, v193, v5, vcc
	v_add_f32_e32 v9, 1.0, v8
	v_cvt_f64_f32_e32 v[4:5], v9
	v_frexp_mant_f32_e32 v10, v9
	v_add_f32_e32 v12, -1.0, v9
	v_frexp_exp_i32_f64_e32 v4, v[4:5]
	v_cmp_gt_f32_e32 vcc, s3, v10
	v_sub_f32_e32 v5, v8, v12
	v_sub_f32_e32 v12, v12, v9
	v_subbrev_co_u32_e32 v4, vcc, 0, v4, vcc
	v_add_f32_e32 v10, 1.0, v12
	v_cvt_f32_i32_e32 v12, v4
	v_sub_u32_e32 v4, 0, v4
	v_add_f32_e32 v5, v5, v10
	v_ldexp_f32 v9, v9, v4
	v_ldexp_f32 v4, v5, v4
	v_add_f32_e32 v5, -1.0, v9
	v_add_f32_e32 v10, 1.0, v9
	v_add_f32_e32 v13, 1.0, v5
	v_add_f32_e32 v14, -1.0, v10
	v_mul_f32_e32 v15, 0x3f317218, v12
	v_sub_f32_e32 v13, v9, v13
	v_sub_f32_e32 v9, v9, v14
	s_mov_b32 s3, 0x3f317218
	v_fma_f32 v14, v12, s3, -v15
	v_add_f32_e32 v13, v4, v13
	v_add_f32_e32 v4, v4, v9
	v_fmac_f32_e32 v14, 0xb102e308, v12
	v_add_f32_e32 v12, v10, v4
	v_rcp_f32_e32 v17, v12
	v_add_f32_e32 v9, v5, v13
	v_add_f32_e32 v16, v15, v14
	v_sub_f32_e32 v10, v10, v12
	v_sub_f32_e32 v5, v5, v9
	v_add_f32_e32 v4, v4, v10
	v_add_f32_e32 v5, v13, v5
	v_sub_f32_e32 v10, v16, v15
	v_mul_f32_e32 v13, v9, v17
	v_sub_f32_e32 v10, v14, v10
	v_mul_f32_e32 v14, v12, v13
	v_fma_f32 v15, v13, v12, -v14
	v_fmac_f32_e32 v15, v13, v4
	v_add_f32_e32 v18, v14, v15
	v_sub_f32_e32 v19, v9, v18
	v_sub_f32_e32 v9, v9, v19
	v_sub_f32_e32 v14, v18, v14
	v_sub_f32_e32 v9, v9, v18
	v_sub_f32_e32 v14, v14, v15
	v_add_f32_e32 v5, v5, v9
	v_add_f32_e32 v5, v14, v5
	v_add_f32_e32 v9, v19, v5
	v_mul_f32_e32 v14, v17, v9
	v_sub_f32_e32 v15, v19, v9
	v_mul_f32_e32 v19, v12, v14
	v_fma_f32 v12, v14, v12, -v19
	v_add_f32_e32 v18, v13, v14
	v_fmac_f32_e32 v12, v14, v4
	v_sub_f32_e32 v13, v18, v13
	v_add_f32_e32 v4, v19, v12
	v_sub_f32_e32 v13, v14, v13
	v_sub_f32_e32 v14, v9, v4
	v_sub_f32_e32 v9, v9, v14
	v_add_f32_e32 v5, v5, v15
	v_sub_f32_e32 v15, v4, v19
	v_sub_f32_e32 v4, v9, v4
	v_sub_f32_e32 v12, v15, v12
	v_add_f32_e32 v4, v5, v4
	v_add_f32_e32 v4, v12, v4
	v_add_f32_e32 v4, v14, v4
	v_mul_f32_e32 v4, v17, v4
	v_add_f32_e32 v4, v13, v4
	v_add_f32_e32 v5, v18, v4
	v_mul_f32_e32 v12, v5, v5
	v_fmamk_f32 v14, v12, 0x3e9b6dac, v177
	v_ldexp_f32 v9, v5, 1
	v_sub_f32_e32 v13, v5, v18
	v_mul_f32_e32 v5, v5, v12
	v_fmaak_f32 v12, v12, v14, 0x3f2aaada
	v_mul_f32_e32 v5, v5, v12
	v_add_f32_e32 v12, v9, v5
	v_sub_f32_e32 v4, v4, v13
	v_sub_f32_e32 v9, v12, v9
	v_ldexp_f32 v4, v4, 1
	v_sub_f32_e32 v5, v5, v9
	v_add_f32_e32 v4, v4, v5
	v_add_f32_e32 v5, v12, v4
	v_add_f32_e32 v9, v16, v5
	v_sub_f32_e32 v12, v5, v12
	v_sub_f32_e32 v4, v4, v12
	v_sub_f32_e32 v12, v9, v16
	v_sub_f32_e32 v5, v5, v12
	v_sub_f32_e32 v12, v9, v12
	v_add_f32_e32 v13, v10, v4
	v_sub_f32_e32 v12, v16, v12
	v_sub_f32_e32 v14, v13, v10
	v_add_f32_e32 v5, v5, v12
	v_sub_f32_e32 v12, v13, v14
	v_add_f32_e32 v5, v13, v5
	v_sub_f32_e32 v10, v10, v12
	v_add_f32_e32 v12, v9, v5
	v_sub_f32_e32 v4, v4, v14
	v_sub_f32_e32 v9, v12, v9
	v_add_f32_e32 v4, v4, v10
	v_sub_f32_e32 v5, v5, v9
	v_add_f32_e32 v4, v4, v5
	s_mov_b32 s3, 0x7f800000
	v_add_f32_e32 v4, v12, v4
	v_cmp_neq_f32_e32 vcc, s3, v8
	s_mov_b32 s3, 0x33800000
	s_nop 0
	v_cndmask_b32_e32 v4, v193, v4, vcc
	v_cmp_lt_f32_e64 vcc, |v8|, s3
	s_nop 1
	v_cndmask_b32_e32 v4, v4, v8, vcc
	v_add_f32_e32 v4, v11, v4
	v_mul_f32_e64 v5, v4, -v3
	ds_bpermute_b32 v8, v104, v5
	v_cmp_nlt_f32_e32 vcc, s79, v2
	s_waitcnt lgkmcnt(0)
	v_fma_f32 v3, v4, -v3, v8
	v_cndmask_b32_e64 v3, v3, v5, s[4:5]
	ds_bpermute_b32 v4, v105, v3
	v_cndmask_b32_e32 v5, 0, v6, vcc
	v_cmp_ngt_f32_e32 vcc, s26, v2
	s_waitcnt lgkmcnt(0)
	v_add_f32_e32 v4, v3, v4
	v_cndmask_b32_e64 v3, v4, v3, s[6:7]
	ds_bpermute_b32 v4, v106, v3
	v_cndmask_b32_e32 v2, v193, v5, vcc
	v_add_f32_e32 v2, 1.0, v2
	v_div_scale_f32 v5, s[42:43], v2, v2, 1.0
	s_waitcnt lgkmcnt(0)
	v_add_f32_e32 v4, v3, v4
	v_cndmask_b32_e64 v3, v4, v3, s[8:9]
	ds_bpermute_b32 v4, v107, v3
	v_rcp_f32_e32 v6, v5
	v_div_scale_f32 v7, vcc, 1.0, v2, 1.0
	s_waitcnt lgkmcnt(0)
	v_add_f32_e32 v4, v3, v4
	v_cndmask_b32_e64 v3, v4, v3, s[10:11]
	ds_bpermute_b32 v4, v108, v3
	v_fma_f32 v8, -v5, v6, 1.0
	v_fmac_f32_e32 v6, v8, v6
	v_mul_f32_e32 v8, v7, v6
	v_fma_f32 v9, -v5, v8, v7
	s_waitcnt lgkmcnt(0)
	v_add_f32_e32 v4, v3, v4
	v_cndmask_b32_e64 v3, v4, v3, s[12:13]
	ds_bpermute_b32 v4, v109, v3
	v_fmac_f32_e32 v8, v9, v6
	v_fma_f32 v5, -v5, v8, v7
	v_div_fmas_f32 v5, v5, v6, v8
	v_div_fixup_f32 v2, v5, v2, 1.0
	s_waitcnt lgkmcnt(0)
	v_add_f32_e32 v4, v3, v4
	v_cndmask_b32_e64 v3, v4, v3, s[14:15]
	ds_write_b32 v117, v3
	ds_write_b32 v118, v2

; #define LAS __attribute__((address_space(3)))
;     const int tid = c.tid, lane = c.lane, wid = c.wid;
;     const int b = item >> 9, h = (item >> 6) & 7, n = item & 63;
;     const int tok0 = b * SEQ + n * 64;
;     LAS float* qc = (LAS float*)c.lds; LAS float* kc = qc + 64 * 68; LAS float* vc = kc + 64 * 68; LAS float* Lm = vc + 64 * 68; LAS float* rhs = Lm + 64 * 68; LAS float* gcs = rhs + 64 * 132; LAS float* bet = gcs + 64;
;     LAS bf16_t* KH = (LAS bf16_t*)(bet + 64); LAS bf16_t* KL = KH + 64 * 72; LAS bf16_t* QH = KL + 64 * 72; LAS bf16_t* QL = QH + 64 * 72;
;     unsigned char* gout = gbase + (size_t)item * GSLOT;
; #pragma unroll
;     for (int which = 0; which < 3; ++which) {
;         const int t = tid >> 3, cg8 = tid & 7; const int col = which * 512 + h * 64 + cg8 * 8;
;         float acc[8];
; #pragma unroll
;         for (int e = 0; e < 8; ++e) acc[e] = 0.f;
; #pragma unroll
;         for (int j = 0; j < 4; ++j) { const int sp = n * 64 + t - 3 + j; const float ok = sp >= 0 ? 1.f : 0.f;
;             const u32x4 xv = xin[which * 4 + j];
;             const f32x4 w0 = *(const f32x4*)(conv_w + j * 1536 + col) * ok, w1 = *(const f32x4*)(conv_w + j * 1536 + col + 4) * ok;
;             acc[0] += w0[0] * bflo(xv.x); acc[1] += w0[1] * bfhi(xv.x); acc[2] += w0[2] * bflo(xv.y); acc[3] += w0[3] * bfhi(xv.y);
;             acc[4] += w1[0] * bflo(xv.z); acc[5] += w1[1] * bfhi(xv.z); acc[6] += w1[2] * bflo(xv.w); acc[7] += w1[3] * bfhi(xv.w); }
; #pragma unroll
;         for (int e = 0; e < 8; ++e) acc[e] = silu_f(acc[e]);
;         if (which == 2) { LAS float* dst = vc + t * 68 + cg8 * 8; *(LAS f32x4*)dst = (f32x4){acc[0], acc[1], acc[2], acc[3]}; *(LAS f32x4*)(dst + 4) = (f32x4){acc[4], acc[5], acc[6], acc[7]}; }
;         else {
;             float ss = (acc[0] * acc[0] + acc[1] * acc[1]) + (acc[2] * acc[2] + acc[3] * acc[3]) + (acc[4] * acc[4] + acc[5] * acc[5]) + (acc[6] * acc[6] + acc[7] * acc[7]);
;             ss += __shfl_xor(ss, 1); ss += __shfl_xor(ss, 2); ss += __shfl_xor(ss, 4);
;             const float sc = (which ? 1.0f : 0.125f) * __builtin_amdgcn_rsqf(ss + 1e-6f);
;             const f32x4 y0 = (f32x4){acc[0], acc[1], acc[2], acc[3]} * sc, y1 = (f32x4){acc[4], acc[5], acc[6], acc[7]} * sc;
;             LAS float* dst = (which ? kc : qc) + t * 68 + cg8 * 8; *(LAS f32x4*)dst = y0; *(LAS f32x4*)(dst + 4) = y1;
.LBB0_1742:
	v_mbcnt_lo_u32_b32 v2, -1, 0
	v_mbcnt_hi_u32_b32 v2, -1, v2
	v_and_b32_e32 v4, 64, v2
	v_xor_b32_e32 v3, 1, v2
	v_add_u32_e32 v5, 64, v4
	v_cmp_lt_i32_e32 vcc, v3, v5
	s_add_u32 s0, s34, 0x10000
	v_writelane_b32 v247, s0, 33
	v_cndmask_b32_e32 v3, v2, v3, vcc
	v_lshlrev_b32_e32 v101, 2, v3
	v_xor_b32_e32 v3, 2, v2
	v_cmp_lt_i32_e32 vcc, v3, v5
	s_addc_u32 s0, s35, 0
	s_add_u32 s71, s34, 0x9800000
	v_cndmask_b32_e32 v3, v2, v3, vcc
	v_lshlrev_b32_e32 v102, 2, v3
	v_xor_b32_e32 v3, 4, v2
	v_cmp_lt_i32_e32 vcc, v3, v5
	s_addc_u32 s95, s35, 0
	s_cmp_lg_u32 s94, 3
	v_cndmask_b32_e32 v3, v2, v3, vcc
	v_lshlrev_b32_e32 v103, 2, v3
	v_add_u32_e32 v3, -1, v2
	v_cmp_lt_i32_e32 vcc, v3, v4
	v_writelane_b32 v247, s0, 34
	s_cselect_b64 s[0:1], -1, 0
	v_cndmask_b32_e32 v3, v3, v2, vcc
	v_lshlrev_b32_e32 v104, 2, v3
	v_add_u32_e32 v3, -2, v2
	v_cmp_lt_i32_e32 vcc, v3, v4
	s_cmp_lg_u32 s94, 4
	s_cselect_b64 s[40:41], -1, 0
	v_cndmask_b32_e32 v3, v3, v2, vcc
	v_lshlrev_b32_e32 v105, 2, v3
	v_add_u32_e32 v3, -4, v2
	v_cmp_lt_i32_e32 vcc, v3, v4
	s_cmp_lg_u32 s94, 5
	s_cselect_b64 s[2:3], -1, 0
	v_cndmask_b32_e32 v3, v3, v2, vcc
	v_lshlrev_b32_e32 v106, 2, v3
	v_add_u32_e32 v3, -8, v2
	v_cmp_lt_i32_e32 vcc, v3, v4
	v_writelane_b32 v247, s2, 35
	s_add_u32 s44, s48, 0x6000
	v_cndmask_b32_e32 v3, v3, v2, vcc
	v_lshlrev_b32_e32 v107, 2, v3
	v_add_u32_e32 v3, -16, v2
	v_writelane_b32 v247, s3, 36
	s_mov_b32 s2, 0x1de00
	v_cmp_lt_i32_e32 vcc, v3, v4
	s_addc_u32 s45, s49, 0
	s_add_i32 s18, s2, 0x100
	s_mov_b32 s2, 0x20200
	v_cndmask_b32_e32 v3, v3, v2, vcc
	s_add_i32 s19, s2, 0x100
	s_mov_b32 s2, 0x19600
	v_lshlrev_b32_e32 v108, 2, v3
	v_subrev_u32_e32 v3, 32, v2
	s_add_i32 s21, s2, 0x100
	s_mov_b32 s2, 0x1ba00
	v_cmp_lt_i32_e32 vcc, v3, v4
	s_add_i32 s22, s2, 0x100
	v_readlane_b32 s24, v247, 26
	v_cndmask_b32_e32 v2, v3, v2, vcc
	s_cmp_lt_u32 s24, 64
	s_mov_b32 s2, 0x19400
	s_mov_b32 s3, 0x19500
	v_lshlrev_b32_e32 v109, 2, v2
	v_lshrrev_b32_e32 v110, 3, v152
	v_lshlrev_b32_e32 v2, 3, v152
	s_cselect_b64 s[46:47], -1, 0
	s_addk_i32 s2, 0x100
	s_addk_i32 s3, 0x100
	s_bfe_u32 s16, s24, 0x10007
	s_bfe_u32 s17, s24, 0x10006
	v_and_b32_e32 v111, 56, v2
	v_mul_u32_u24_e32 v5, 0x48, v110
	s_cmp_le_u32 s16, s17
	v_lshlrev_b32_e32 v5, 1, v5
	v_lshlrev_b32_e32 v82, 1, v111
	s_cselect_b64 s[48:49], -1, 0
	s_cmpk_gt_u32 s24, 0xff
	v_add3_u32 v113, s18, v5, v82
	v_add3_u32 v114, s19, v5, v82
	v_add3_u32 v115, s21, v5, v82
	v_add3_u32 v116, s22, v5, v82
	v_lshlrev_b32_e32 v5, 2, v202
	s_cselect_b64 s[88:89], -1, 0
	s_cmpk_lt_u32 s24, 0x100
	v_add_u32_e32 v117, s2, v5
	v_add_u32_e32 v118, s3, v5
	v_lshrrev_b32_e32 v5, 5, v202
	v_and_b32_e32 v6, 31, v152
	s_cselect_b32 s18, s21, s18
	s_cselect_b32 s19, s22, s19
	s_lshl_b32 s23, s16, 5
	v_or_b32_e32 v7, s23, v6
	v_lshlrev_b32_e32 v8, 3, v5
	v_lshl_or_b32 v9, s17, 5, v6
	v_lshl_or_b32 v5, v5, 2, s23
	v_mul_u32_u24_e32 v7, 0x48, v7
	v_mul_u32_u24_e32 v10, 0x48, v9
	v_cmp_gt_u32_e64 s[4:5], v5, v9
	v_add_lshl_u32 v7, v7, v8, 1
	v_add_lshl_u32 v8, v10, v8, 1
	v_writelane_b32 v247, s4, 39
	v_or_b32_e32 v10, 1, v5
	v_lshl_add_u32 v132, v10, 2, s2
	v_writelane_b32 v247, s5, 40
	v_cmp_lt_u32_e64 s[4:5], v10, v9
	v_or_b32_e32 v10, 2, v5
	v_lshl_add_u32 v133, v10, 2, s2
	v_writelane_b32 v247, s4, 37
	v_add_u32_e32 v121, s18, v8
	v_add_u32_e32 v122, s19, v8
	v_writelane_b32 v247, s5, 38
	v_cmp_gt_u32_e64 s[4:5], v10, v9
	v_add_u32_e32 v8, 32, v7
	v_add_u32_e32 v123, s21, v8
	v_writelane_b32 v247, s4, 41
	v_add_u32_e32 v124, s22, v8
	v_add_u32_e32 v8, 64, v7
	v_writelane_b32 v247, s5, 42
	v_cmp_lt_u32_e64 s[4:5], v10, v9
	v_or_b32_e32 v10, 3, v5
	v_lshl_add_u32 v134, v10, 2, s2
	v_writelane_b32 v247, s4, 43
	v_add_u32_e32 v119, s21, v7
	v_add_u32_e32 v120, s22, v7
	v_writelane_b32 v247, s5, 44
	v_cmp_gt_u32_e64 s[4:5], v10, v9
	v_add_u32_e32 v125, s21, v8
	v_add_u32_e32 v126, s22, v8
	v_writelane_b32 v247, s4, 45
	v_add_u32_e32 v7, 0x60, v7
	v_lshl_add_u32 v131, v5, 2, s2
	v_writelane_b32 v247, s5, 46
	v_cmp_lt_u32_e64 s[4:5], v10, v9
	v_or_b32_e32 v10, 8, v5
	v_lshl_add_u32 v135, v10, 2, s2
	v_writelane_b32 v247, s4, 47
	v_cmp_lt_u32_e64 s[42:43], v5, v9
	v_mul_u32_u24_e32 v8, 0x110, v5
	v_writelane_b32 v247, s5, 48
	v_cmp_gt_u32_e64 s[4:5], v10, v9
	v_add_u32_e32 v127, s21, v7
	s_bfe_u32 s21, s24, 0x20006
	v_writelane_b32 v247, s4, 49
	s_brev_b32 s21, s21
	s_lshr_b32 s21, s21, 19
	v_writelane_b32 v247, s5, 50
	v_cmp_lt_u32_e64 s[4:5], v10, v9
	v_or_b32_e32 v10, 9, v5
	v_lshl_add_u32 v136, v10, 2, s2
	v_writelane_b32 v247, s4, 51
	v_lshlrev_b32_e32 v86, 4, v202
	s_cmp_eq_u32 s16, s17
	v_writelane_b32 v247, s5, 52
	v_cmp_gt_u32_e64 s[4:5], v10, v9
	s_mov_b32 s17, 0x11000
	v_or_b32_e32 v88, s21, v86
	v_writelane_b32 v247, s4, 53
	v_and_or_b32 v15, v110, 32, v6
	v_lshrrev_b32_e32 v16, 2, v152
	v_writelane_b32 v247, s5, 54
	v_cmp_lt_u32_e64 s[4:5], v10, v9
	v_or_b32_e32 v10, 10, v5
	v_lshl_add_u32 v137, v10, 2, s2
	v_writelane_b32 v247, s4, 55
	v_lshlrev_b32_e32 v21, 2, v15
	v_and_b32_e32 v24, 0x60, v110
	v_writelane_b32 v247, s5, 56
	v_cmp_gt_u32_e64 s[4:5], v10, v9
	v_and_b32_e32 v16, 48, v16
	v_and_b32_e32 v17, 4, v110
	v_writelane_b32 v247, s4, 57
	v_add_u32_e32 v22, 0x100, v21
	v_add_u32_e32 v165, s2, v21
	v_writelane_b32 v247, s5, 58
	v_cmp_lt_u32_e64 s[4:5], v10, v9
	v_or_b32_e32 v10, 11, v5
	v_lshl_add_u32 v138, v10, 2, s2
	v_writelane_b32 v247, s4, 59
	v_or_b32_e32 v6, v24, v6
	v_or_b32_e32 v18, v16, v17
	v_writelane_b32 v247, s5, 60
	v_cmp_gt_u32_e64 s[4:5], v10, v9
	v_lshlrev_b32_e32 v16, 2, v16
	v_lshlrev_b32_e32 v17, 2, v17
	v_writelane_b32 v247, s4, 61
	v_add_u32_e32 v128, s22, v7
	v_lshlrev_b32_e32 v7, 2, v9
; #define LAS __attribute__((address_space(3)))
; DI float fexp2(float x) { return __builtin_amdgcn_exp2f(x); }
; DI int crow(int r, int hi) { return (r & 3) + 8 * (r >> 2) + 4 * hi; }
;     ...
;             const int i = 32 * it + l31; const float gi = gcs[i], bi = bet[i];
; #pragma unroll
;             for (int r = 0; r < 16; ++r) { const int j = 32 * jt + crow(r, hi); const float d = fexp2((gi - gcs[j]) * 1.4426950408889634f);
;                 if (isqk) acc[r] = (j <= i) ? acc[r] * d : 0.f; else Lm[j * 68 + i] = (j < i) ? bi * acc[r] * d : 0.f; }
;             if (isqk) {
; #pragma unroll
;                 for (int sx = 0; sx < 2; ++sx) { const bf16x8 pk = pack8(acc, sx); *(u32x4*)(gout + 2 * 8192 + ((it * 4 + 2 * jt + sx) * 64 + lane) * 16) = __builtin_bit_cast(u32x4, pk); } }
;             else if (jt == it) {
;                 const int bb = 2 * jt + ((lane >> 4) & 1), col = lane & 15;
;                 float y[16];
; #pragma unroll
;                 for (int ii = 0; ii < 16; ++ii) y[ii] = (ii == col) ? 1.f : 0.f;
; #pragma unroll
;                 for (int j = 0; j < 15; ++j) { const float yj = y[j];
; #pragma unroll
;                     for (int q4 = (j + 1) / 4; q4 < 4; ++q4) { const f32x4 l4 = *(const LAS f32x4*)(Lm + (16 * bb + j) * 68 + 16 * bb + 4 * q4);
; #pragma unroll
;                         for (int e = 0; e < 4; ++e) if (4 * q4 + e > j) y[4 * q4 + e] -= l4[e] * yj; } }
; #pragma unroll
;                 for (int ii = 0; ii < 16; ++ii) DIV[bb * 320 + ii * 20 + col] = y[ii];
	v_writelane_b32 v247, s5, 62
	v_cmp_lt_u32_e64 s[4:5], v10, v9
	v_or_b32_e32 v10, 16, v5
	v_lshl_add_u32 v139, v10, 2, s2
	v_writelane_b32 v247, s4, 63
	v_mov_b32_e32 v2, 0x100
	v_readlane_b32 s16, v247, 25
	v_writelane_b32 v246, s5, 0
	v_cmp_gt_u32_e64 s[4:5], v10, v9
	v_lshlrev_b32_e32 v90, 4, v152
	v_lshl_add_u32 v3, v111, 2, v2
	v_writelane_b32 v246, s4, 1
	v_lshlrev_b32_e32 v19, 2, v18
	v_add_u32_e32 v20, 0x100, v19
	v_writelane_b32 v246, s5, 2
	v_cmp_lt_u32_e64 s[4:5], v10, v9
	v_or_b32_e32 v10, 17, v5
	v_lshl_add_u32 v140, v10, 2, s2
	v_writelane_b32 v246, s4, 3
	v_add_u32_e32 v166, s2, v19
	v_lshrrev_b32_e32 v19, 4, v202
	v_writelane_b32 v246, s5, 4
	v_cmp_gt_u32_e64 s[4:5], v10, v9
	v_lshrrev_b32_e32 v170, 7, v152
	v_lshlrev_b32_e32 v23, 2, v19
	v_writelane_b32 v246, s4, 5
	s_movk_i32 s20, 0x110
	v_mul_u32_u24_e32 v4, 0x110, v110
	v_writelane_b32 v246, s5, 6
	v_cmp_lt_u32_e64 s[4:5], v10, v9
	v_or_b32_e32 v10, 18, v5
	v_lshl_add_u32 v141, v10, 2, s2
	v_writelane_b32 v246, s4, 7
	v_mov_b32_e32 v83, 0
	v_add_u32_e32 v129, s2, v7
	v_writelane_b32 v246, s5, 8
	v_cmp_gt_u32_e64 s[4:5], v10, v9
	v_add_u32_e32 v130, s3, v7
	v_add_u32_e32 v7, 0x100, v7
	v_writelane_b32 v246, s4, 9
	v_mul_u32_u24_e32 v15, 0x110, v15
	v_mul_u32_u24_e32 v18, 0x110, v18
	v_writelane_b32 v246, s5, 10
	v_cmp_lt_u32_e64 s[4:5], v10, v9
	v_or_b32_e32 v10, 19, v5
	v_lshl_add_u32 v142, v10, 2, s2
	v_writelane_b32 v246, s4, 11
	s_movk_i32 s22, 0x1ff
	s_mov_b32 s25, 0
	v_writelane_b32 v246, s5, 12
	v_cmp_gt_u32_e64 s[4:5], v10, v9
	v_mad_u32_u24 v112, v110, s20, v3
	v_cmp_eq_u32_e64 s[58:59], 0, v202
	v_writelane_b32 v246, s4, 13
	v_cmp_gt_u32_e64 s[56:57], 2, v202
	v_cmp_gt_u32_e64 s[74:75], 4, v202
	v_writelane_b32 v246, s5, 14
	v_cmp_lt_u32_e64 s[4:5], v10, v9
	v_or_b32_e32 v10, 24, v5
	v_lshl_add_u32 v143, v10, 2, s2
	v_writelane_b32 v246, s4, 15
	v_cmp_gt_u32_e64 s[76:77], 8, v202
	v_cmp_gt_u32_e64 s[78:79], 16, v202
	v_writelane_b32 v246, s5, 16
	v_cmp_gt_u32_e64 s[4:5], v10, v9
	v_cmp_gt_u32_e64 s[60:61], 32, v202
	v_lshl_add_u64 v[84:85], s[36:37], 0, v[82:83]
	v_writelane_b32 v246, s4, 17
	v_mov_b32_e32 v89, v83
	v_mov_b32_e32 v87, v83
	v_writelane_b32 v246, s5, 18
	v_cmp_lt_u32_e64 s[4:5], v10, v9
	v_or_b32_e32 v10, 25, v5
	v_lshl_add_u32 v144, v10, 2, s2
	v_writelane_b32 v246, s4, 19
	v_and_b32_e32 v92, 0x1ff0, v90
	v_mov_b32_e32 v93, v83
	v_writelane_b32 v246, s5, 20
	v_cmp_gt_u32_e64 s[4:5], v10, v9
	v_add_u32_e32 v167, 32, v166
	v_mov_b32_e32 v91, v83
	v_writelane_b32 v246, s4, 21
	v_cmp_lt_u32_e64 s[82:83], s22, v152
	v_add_u32_e32 v173, 0x200, v152
	v_writelane_b32 v246, s5, 22
	v_cmp_lt_u32_e64 s[4:5], v10, v9
	v_or_b32_e32 v10, 26, v5
	v_lshl_add_u32 v145, v10, 2, s2
	v_writelane_b32 v246, s4, 23
	v_or_b32_e32 v5, 27, v5
	v_lshl_add_u32 v146, v5, 2, s2
	v_writelane_b32 v246, s5, 24
	v_cmp_gt_u32_e64 s[4:5], v10, v9
	s_mov_b32 s23, 0xbfb8aa3b
	s_mov_b64 s[62:63], 0x4000
	v_writelane_b32 v246, s4, 25
	v_add_u32_e32 v176, v3, v4
	s_mov_b32 s96, 0x42ce8ed0
	v_writelane_b32 v246, s5, 26
	v_cmp_lt_u32_e64 s[4:5], v10, v9
	v_and_b32_e32 v10, 15, v152
	v_cmp_eq_u32_e32 vcc, 0, v10
	v_writelane_b32 v246, s4, 27
	v_lshlrev_b32_e32 v12, 2, v10
	v_cndmask_b32_e64 v147, 0, 1.0, vcc
	v_cmp_eq_u32_e32 vcc, 1, v10
	v_writelane_b32 v246, s5, 28
	v_cmp_gt_u32_e64 s[4:5], v5, v9
	v_cndmask_b32_e64 v148, 0, 1.0, vcc
	v_cmp_eq_u32_e32 vcc, 2, v10
	v_writelane_b32 v246, s4, 29
	s_mov_b32 s97, 0xc2b17218
	v_cndmask_b32_e64 v149, 0, 1.0, vcc
	v_cmp_eq_u32_e32 vcc, 3, v10
	v_writelane_b32 v246, s5, 30
	v_cmp_lt_u32_e64 s[4:5], v5, v9
	v_cndmask_b32_e64 v150, 0, 1.0, vcc
	v_cmp_eq_u32_e32 vcc, 4, v10
	v_writelane_b32 v246, s4, 31
	v_lshrrev_b32_e32 v5, 4, v152
	v_cndmask_b32_e64 v151, 0, 1.0, vcc
	v_cmp_eq_u32_e32 vcc, 5, v10
	v_writelane_b32 v246, s5, 32
	s_cselect_b64 s[4:5], -1, 0
	v_cndmask_b32_e64 v153, 0, 1.0, vcc
	v_cmp_eq_u32_e32 vcc, 6, v10
	s_addk_i32 s17, 0x100
	s_and_b32 s21, s24, 0xffffffc0
	v_cndmask_b32_e64 v154, 0, 1.0, vcc
	v_cmp_eq_u32_e32 vcc, 7, v10
; #define LAS __attribute__((address_space(3)))
;     ...
;     LAS float* qc = (LAS float*)c.lds; LAS float* kc = qc + 64 * 68; LAS float* vc = kc + 64 * 68; LAS float* Lm = vc + 64 * 68; LAS float* rhs = Lm + 64 * 68; LAS float* gcs = rhs + 64 * 132; LAS float* bet = gcs + 64;
;     LAS bf16_t* KH = (LAS bf16_t*)(bet + 64); LAS bf16_t* KL = KH + 64 * 72; LAS bf16_t* QH = KL + 64 * 72; LAS bf16_t* QL = QH + 64 * 72;
;     unsigned char* gout = gbase + (size_t)item * GSLOT;
; #pragma unroll
;     for (int which = 0; which < 3; ++which) {
;         const int t = tid >> 3, cg8 = tid & 7; const int col = which * 512 + h * 64 + cg8 * 8;
;         float acc[8];
; #pragma unroll
;         for (int e = 0; e < 8; ++e) acc[e] = 0.f;
; #pragma unroll
;         for (int j = 0; j < 4; ++j) { const int sp = n * 64 + t - 3 + j; const float ok = sp >= 0 ? 1.f : 0.f;
;             const u32x4 xv = xin[which * 4 + j];
;             const f32x4 w0 = *(const f32x4*)(conv_w + j * 1536 + col) * ok, w1 = *(const f32x4*)(conv_w + j * 1536 + col + 4) * ok;
	s_add_i32 s21, s17, s21
	v_add_u32_e32 v21, s21, v12
	v_cndmask_b32_e64 v155, 0, 1.0, vcc
	v_cmp_eq_u32_e32 vcc, 8, v10
	s_movk_i32 s21, 0x210
	v_mov_b32_e32 v25, s17
	v_cndmask_b32_e64 v156, 0, 1.0, vcc
	v_cmp_eq_u32_e32 vcc, 9, v10
	v_mad_u32_u24 v6, v6, s21, v25
	v_bfe_u32 v9, v152, 4, 1
	v_cndmask_b32_e64 v157, 0, 1.0, vcc
	v_cmp_eq_u32_e32 vcc, 10, v10
	v_add3_u32 v169, v6, v16, v17
	v_lshlrev_b32_e32 v16, 1, v152
	v_cndmask_b32_e64 v158, 0, 1.0, vcc
	v_cmp_eq_u32_e32 vcc, 11, v10
	v_and_or_b32 v9, s16, 2, v9
	s_mov_b32 s16, 0x22600
	v_cndmask_b32_e64 v159, 0, 1.0, vcc
	v_cmp_eq_u32_e32 vcc, 12, v10
	v_and_b32_e32 v5, 4, v5
	v_and_b32_e32 v6, 0x80, v152
	v_and_b32_e32 v16, 0x7c, v16
	v_cndmask_b32_e64 v160, 0, 1.0, vcc
	v_cmp_eq_u32_e32 vcc, 13, v10
	v_lshl_add_u32 v2, v9, 6, v2
	v_mul_u32_u24_e32 v11, 0x1100, v9
	v_mul_u32_u24_e32 v9, 0x500, v9
	s_addk_i32 s16, 0x100
	v_add3_u32 v6, s17, v6, v16
	v_and_b32_e32 v16, 16, v90
	v_or_b32_e32 v25, 1, v5
	v_or_b32_e32 v27, 2, v5
	v_or_b32_e32 v29, 3, v5
	v_cndmask_b32_e64 v161, 0, 1.0, vcc
	v_cmp_eq_u32_e32 vcc, 14, v10
	v_add3_u32 v164, s16, v9, v12
	v_and_b32_e32 v9, 0x7f, v152
	v_or3_b32 v17, v5, v16, v24
	v_or3_b32 v26, v16, v25, v24
	v_or3_b32 v28, v16, v27, v24
	v_or3_b32 v30, v16, v29, v24
	v_or_b32_e32 v16, 8, v16
	v_cndmask_b32_e64 v162, 0, 1.0, vcc
	v_cmp_eq_u32_e32 vcc, 15, v10
	v_cmp_lt_u32_e64 s[80:81], 63, v9
	v_lshlrev_b32_e32 v9, 2, v9
	v_mul_u32_u24_e32 v10, 0x50, v10
	v_or3_b32 v5, v5, v16, v24
	v_or3_b32 v25, v25, v16, v24
	v_or3_b32 v27, v27, v16, v24
	v_or3_b32 v16, v29, v16, v24
	v_lshlrev_b32_e32 v24, 2, v170
	v_add_u32_e32 v13, 0x100, v9
	v_add_u32_e32 v14, s17, v9
	v_add_u32_e32 v12, 0x100, v12
	v_add3_u32 v168, s16, v10, v23
	v_mul_u32_u24_e32 v10, 0x840, v19
	v_mul_u32_u24_e32 v23, 0x210, v19
	v_mul_u32_u24_e32 v19, 0x110, v19
	v_mul_u32_u24_e32 v17, 0x210, v17
	v_mul_u32_u24_e32 v26, 0x210, v26
	v_mul_u32_u24_e32 v28, 0x210, v28
	v_mul_u32_u24_e32 v30, 0x210, v30
	v_mul_u32_u24_e32 v5, 0x210, v5
	v_mul_u32_u24_e32 v25, 0x210, v25
	v_mul_u32_u24_e32 v27, 0x210, v27
	v_mul_u32_u24_e32 v16, 0x210, v16
	v_add_u32_e32 v171, s3, v24
	v_mul_u32_u24_e32 v29, 0x110, v170
	v_add_u32_e32 v172, s2, v24
	v_mul_u32_u24_e32 v24, 0x210, v170
	s_mov_b32 s16, 0x194fc
	v_writelane_b32 v246, s4, 33
	v_cndmask_b32_e64 v163, 0, 1.0, vcc
	v_add_u32_e32 v174, 0x4300, v9
	v_or_b32_e32 v175, 0x11000, v9
	s_mov_b32 s2, 0x3fb8aa3b
	s_mov_b32 s3, 0xc2ce8ed0
	s_mov_b32 s64, 0x42b17218
	v_mov_b32_e32 v177, 0x3ecc95a3
	s_add_i32 s65, s16, 0x100
	s_movk_i32 s72, 0x1a00
	v_add_u32_e32 v178, v2, v11
	v_add_u32_e32 v179, v14, v24
	v_add_u32_e32 v180, v22, v18
	v_add_u32_e32 v181, v20, v15
	v_add_u32_e32 v182, v21, v23
	v_add_u32_e32 v183, v21, v10
	v_add_u32_e32 v184, v12, v19
	v_add_u32_e32 v185, v6, v17
	v_add_u32_e32 v186, v6, v26
	v_add_u32_e32 v187, v6, v28
	v_add_u32_e32 v188, v6, v30
	v_add_u32_e32 v189, v6, v5
	v_add_u32_e32 v190, v6, v25
	v_add_u32_e32 v191, v6, v27
	v_add_u32_e32 v192, v6, v16
	v_mov_b32_e32 v193, 0x7f800000
	v_add_u32_e32 v194, v7, v8
	v_add_u32_e32 v195, v13, v29
	v_and_b32_e32 v240, 15, v152
	v_lshlrev_b32_e32 v240, 4, v240
	v_bfe_u32 v241, v152, 4, 2
	v_bfe_u32 v242, v152, 6, 2
	v_lshrrev_b32_e32 v243, 8, v152
	v_cmp_gt_u32_e32 vcc, 3, v241
	s_and_saveexec_b64 s[98:99], vcc
	s_bfe_u32 s100, s70, 0x30006
	v_lshlrev_b32_e32 v237, 2, v243
	v_xor_b32_e32 v237, s100, v237
	v_mul_u32_u24_e32 v236, 0x1800, v242
	v_lshl_add_u32 v236, v241, 11, v236
	v_add_u32_e32 v236, v236, v240
	v_lshl_add_u32 v236, v237, 8, v236
	v_mul_u32_u24_e32 v237, 0xc00, v243
	v_mul_u32_u24_e32 v242, 0x300, v242
	v_add_u32_e32 v237, v237, v242
	v_lshl_add_u32 v237, v241, 8, v237
	v_add_u32_e32 v237, v237, v240
	v_add_u32_e32 v243, 0x24100, v237
	global_load_dwordx4 v[236:239], v236, s[44:45]
	s_waitcnt vmcnt(0)
	ds_write_b128 v243, v[236:239]
	s_mov_b64 exec, s[98:99]
	s_waitcnt lgkmcnt(0)
	s_barrier
	s_mov_b32 s68, s70
	v_writelane_b32 v246, s5, 34
	s_branch .LBB0_1745

; #define LAS __attribute__((address_space(3)))
; DI float bflo(unsigned w) { return __uint_as_float(w << 16); }
; DI float bfhi(unsigned w) { return __uint_as_float(w & 0xffff0000u); }
; DI float silu_f(float g) { return g * frcp(1.f + fexp2(-1.4426950408889634f * g)); }
;     ...
;     for (int which = 0; which < 3; ++which) {
;         const int t = tid >> 3, cg8 = tid & 7; const int col = which * 512 + h * 64 + cg8 * 8;
;         float acc[8];
; #pragma unroll
;         for (int e = 0; e < 8; ++e) acc[e] = 0.f;
; #pragma unroll
;         for (int j = 0; j < 4; ++j) { const int sp = n * 64 + t - 3 + j; const float ok = sp >= 0 ? 1.f : 0.f;
;             const u32x4 xv = xin[which * 4 + j];
;             const f32x4 w0 = *(const f32x4*)(conv_w + j * 1536 + col) * ok, w1 = *(const f32x4*)(conv_w + j * 1536 + col + 4) * ok;
;             acc[0] += w0[0] * bflo(xv.x); acc[1] += w0[1] * bfhi(xv.x); acc[2] += w0[2] * bflo(xv.y); acc[3] += w0[3] * bfhi(xv.y);
;             acc[4] += w1[0] * bflo(xv.z); acc[5] += w1[1] * bfhi(xv.z); acc[6] += w1[2] * bflo(xv.w); acc[7] += w1[3] * bfhi(xv.w); }
; #pragma unroll
;         for (int e = 0; e < 8; ++e) acc[e] = silu_f(acc[e]);
;         if (which == 2) { LAS float* dst = vc + t * 68 + cg8 * 8; *(LAS f32x4*)dst = (f32x4){acc[0], acc[1], acc[2], acc[3]}; *(LAS f32x4*)(dst + 4) = (f32x4){acc[4], acc[5], acc[6], acc[7]}; }
;         else {
;             float ss = (acc[0] * acc[0] + acc[1] * acc[1]) + (acc[2] * acc[2] + acc[3] * acc[3]) + (acc[4] * acc[4] + acc[5] * acc[5]) + (acc[6] * acc[6] + acc[7] * acc[7]);
;             ss += __shfl_xor(ss, 1); ss += __shfl_xor(ss, 2); ss += __shfl_xor(ss, 4);
.LBB0_1745:
	s_lshl_b32 s16, s68, 6
	s_and_b32 s16, s16, 0xfc0
	v_add_u32_e32 v2, s16, v110
	v_cmp_lt_u32_e32 vcc, 2, v2
	s_bfe_u32 s24, s68, 0x30006
	s_bfe_u32 s100, s70, 0x30006
	s_xor_b32 s100, s100, s24
	s_mul_i32 s100, s100, 0x300
	v_lshlrev_b32_e32 v255, 2, v111
	v_add_u32_e32 v255, s100, v255
	v_add_u32_e32 v255, 0x24100, v255
	s_mov_b64 s[16:17], 0x1800
	v_cndmask_b32_e64 v26, 0, 1.0, vcc
	v_cmp_lt_u32_e32 vcc, 1, v2
	s_waitcnt vmcnt(0)
	v_lshlrev_b32_e32 v208, 16, v54
	v_and_b32_e32 v209, 0xffff0000, v54
	v_cndmask_b32_e64 v24, 0, 1.0, vcc
	v_cmp_eq_u32_e32 vcc, 0, v2
	v_lshlrev_b32_e32 v2, 2, v111
	v_lshl_or_b32 v82, s24, 8, v2
	ds_read_b128 v[18:21], v255 offset:0
	ds_read_b128 v[2:5], v255 offset:16
	v_lshl_add_u64 v[14:15], s[44:45], 0, v[82:83]
	v_cndmask_b32_e64 v22, 1.0, 0, vcc
	s_waitcnt lgkmcnt(0)
	v_pk_mul_f32 v[18:19], v[26:27], v[18:19] op_sel_hi:[0,1]
	v_pk_mul_f32 v[8:9], v[4:5], v[26:27] op_sel_hi:[1,0]
	v_lshl_add_u64 v[4:5], v[14:15], 0, s[16:17]
	s_movk_i32 s16, 0x1000
	v_pk_mul_f32 v[10:11], v[2:3], v[26:27] op_sel_hi:[1,0]
	v_add_co_u32_e32 v2, vcc, s16, v14
	s_mov_b64 s[16:17], 0x3000
	s_nop 0
	v_addc_co_u32_e32 v3, vcc, 0, v15, vcc
	ds_read_b128 v[28:31], v255 offset:768
	s_nop 0
	ds_read_b128 v[4:7], v255 offset:784
	v_lshl_add_u64 v[32:33], v[14:15], 0, s[16:17]
	s_movk_i32 s16, 0x3000
	v_pk_mul_f32 v[20:21], v[26:27], v[20:21] op_sel_hi:[0,1]
	s_waitcnt lgkmcnt(0)
	v_pk_mul_f32 v[28:29], v[24:25], v[28:29] op_sel_hi:[0,1]
	v_pk_mul_f32 v[12:13], v[6:7], v[24:25] op_sel_hi:[1,0]
	v_add_co_u32_e32 v6, vcc, s16, v14
	s_movk_i32 s16, 0x4000
	s_nop 0
	v_addc_co_u32_e32 v7, vcc, 0, v15, vcc
	v_pk_mul_f32 v[16:17], v[4:5], v[24:25] op_sel_hi:[1,0]
	v_add_co_u32_e32 v4, vcc, s16, v14
	s_mov_b64 s[16:17], 0x4800
	s_nop 0
	v_addc_co_u32_e32 v5, vcc, 0, v15, vcc
	ds_read_b128 v[94:97], v255 offset:1536
	ds_read_b128 v[196:199], v255 offset:1552
	v_lshl_add_u64 v[200:201], v[14:15], 0, s[16:17]
	v_pk_mul_f32 v[30:31], v[24:25], v[30:31] op_sel_hi:[0,1]
	s_mov_b64 s[16:17], 0x2000
	s_waitcnt lgkmcnt(0)
	v_pk_mul_f32 v[94:95], v[22:23], v[94:95] op_sel_hi:[0,1]
	v_pk_mul_f32 v[32:33], v[198:199], v[22:23] op_sel_hi:[1,0]
	v_pk_mul_f32 v[98:99], v[196:197], v[22:23] op_sel_hi:[1,0]
	ds_read_b128 v[196:199], v255 offset:2304
	ds_read_b128 v[204:207], v255 offset:2320
	v_lshlrev_b32_e32 v200, 16, v70
	v_and_b32_e32 v201, 0xffff0000, v70
	v_pk_fma_f32 v[18:19], v[18:19], v[200:201], 0 op_sel_hi:[1,1,0]
	v_lshlrev_b32_e32 v200, 16, v74
	v_and_b32_e32 v201, 0xffff0000, v74
	v_pk_fma_f32 v[18:19], v[28:29], v[200:201], v[18:19]
	v_lshlrev_b32_e32 v28, 16, v58
	v_and_b32_e32 v29, 0xffff0000, v58
	v_pk_fma_f32 v[18:19], v[94:95], v[28:29], v[18:19]
	v_lshlrev_b32_e32 v28, 16, v78
	v_and_b32_e32 v29, 0xffff0000, v78
	v_pk_mul_f32 v[96:97], v[22:23], v[96:97] op_sel_hi:[0,1]
	s_waitcnt lgkmcnt(0)
	v_pk_fma_f32 v[18:19], v[196:197], v[28:29], v[18:19]
	s_nop 0
	v_mul_f32_e32 v23, 0xbfb8aa3b, v18
	v_exp_f32_e32 v23, v23
	s_nop 0
	v_add_f32_e32 v23, 1.0, v23
	v_rcp_f32_e32 v28, v23
	v_mul_f32_e32 v23, 0xbfb8aa3b, v19
	v_exp_f32_e32 v23, v23
	s_nop 0
	v_add_f32_e32 v23, 1.0, v23
	v_rcp_f32_e32 v29, v23
	s_nop 0
	v_pk_mul_f32 v[28:29], v[18:19], v[28:29]
	v_lshlrev_b32_e32 v18, 16, v71
	v_and_b32_e32 v19, 0xffff0000, v71
	v_pk_fma_f32 v[18:19], v[20:21], v[18:19], 0 op_sel_hi:[1,1,0]
	v_lshlrev_b32_e32 v20, 16, v75
	v_and_b32_e32 v21, 0xffff0000, v75
	v_pk_fma_f32 v[18:19], v[30:31], v[20:21], v[18:19]
	v_lshlrev_b32_e32 v20, 16, v59
	v_and_b32_e32 v21, 0xffff0000, v59
	v_pk_fma_f32 v[18:19], v[96:97], v[20:21], v[18:19]
	v_lshlrev_b32_e32 v20, 16, v79
	v_and_b32_e32 v21, 0xffff0000, v79
	v_pk_fma_f32 v[18:19], v[198:199], v[20:21], v[18:19]
	s_nop 0
	v_mul_f32_e32 v20, 0xbfb8aa3b, v18
	v_mul_f32_e32 v21, 0xbfb8aa3b, v19
	v_exp_f32_e32 v20, v20
	v_exp_f32_e32 v21, v21
	v_add_f32_e32 v20, 1.0, v20
	v_add_f32_e32 v21, 1.0, v21
	v_rcp_f32_e32 v20, v20
	v_rcp_f32_e32 v21, v21
	s_nop 0
	v_pk_mul_f32 v[20:21], v[18:19], v[20:21]
	v_lshlrev_b32_e32 v18, 16, v72
	v_and_b32_e32 v19, 0xffff0000, v72
	v_pk_fma_f32 v[10:11], v[10:11], v[18:19], 0 op_sel_hi:[1,1,0]
	v_lshlrev_b32_e32 v18, 16, v76
	v_and_b32_e32 v19, 0xffff0000, v76
	v_pk_fma_f32 v[10:11], v[16:17], v[18:19], v[10:11]
	v_lshlrev_b32_e32 v16, 16, v60
	v_and_b32_e32 v17, 0xffff0000, v60
	v_pk_fma_f32 v[10:11], v[98:99], v[16:17], v[10:11]
	v_lshlrev_b32_e32 v16, 16, v80
	v_and_b32_e32 v17, 0xffff0000, v80
	v_pk_fma_f32 v[10:11], v[204:205], v[16:17], v[10:11]
	s_nop 0
	v_mul_f32_e32 v16, 0xbfb8aa3b, v10
	v_mul_f32_e32 v17, 0xbfb8aa3b, v11
	v_exp_f32_e32 v16, v16
	v_exp_f32_e32 v17, v17
	v_add_f32_e32 v16, 1.0, v16
	v_add_f32_e32 v17, 1.0, v17
	v_rcp_f32_e32 v16, v16
	v_rcp_f32_e32 v17, v17
	s_nop 0
	v_pk_mul_f32 v[30:31], v[10:11], v[16:17]
	v_lshlrev_b32_e32 v10, 16, v73
	v_and_b32_e32 v11, 0xffff0000, v73
	v_pk_fma_f32 v[8:9], v[8:9], v[10:11], 0 op_sel_hi:[1,1,0]
	v_lshlrev_b32_e32 v10, 16, v77
	v_and_b32_e32 v11, 0xffff0000, v77
	v_pk_fma_f32 v[8:9], v[12:13], v[10:11], v[8:9]
	v_lshlrev_b32_e32 v10, 16, v61
	v_and_b32_e32 v11, 0xffff0000, v61
	v_pk_fma_f32 v[8:9], v[32:33], v[10:11], v[8:9]
	v_lshlrev_b32_e32 v10, 16, v81
	v_and_b32_e32 v11, 0xffff0000, v81
	v_pk_fma_f32 v[8:9], v[206:207], v[10:11], v[8:9]
	v_mov_b32_e32 v17, v31
	v_mul_f32_e32 v10, 0xbfb8aa3b, v9
	v_exp_f32_e32 v10, v10
	s_nop 0
	v_add_f32_e32 v10, 1.0, v10
	v_rcp_f32_e32 v11, v10
	v_mul_f32_e32 v10, 0xbfb8aa3b, v8
	v_exp_f32_e32 v10, v10
	s_nop 0
	v_add_f32_e32 v10, 1.0, v10
	v_rcp_f32_e32 v10, v10
	s_nop 0
	v_pk_mul_f32 v[12:13], v[8:9], v[10:11]
	v_mov_b32_e32 v10, v29
	v_mov_b32_e32 v11, v21
	v_mov_b32_e32 v8, v28
	v_mov_b32_e32 v9, v20
	v_pk_mul_f32 v[10:11], v[10:11], v[10:11]
	v_mov_b32_e32 v16, v13
	v_pk_fma_f32 v[8:9], v[8:9], v[8:9], v[10:11]
	v_mov_b32_e32 v10, v12
	v_mov_b32_e32 v11, v30
	v_pk_mul_f32 v[16:17], v[16:17], v[16:17]
	v_add_f32_e32 v8, v8, v9
	v_pk_fma_f32 v[10:11], v[10:11], v[10:11], v[16:17]
	s_nop 0
	v_add_f32_e32 v8, v11, v8
	v_add_f32_e32 v8, v10, v8
	ds_bpermute_b32 v9, v101, v8
	s_waitcnt lgkmcnt(0)
; #define LAS __attribute__((address_space(3)))
; DI unsigned pk2(float lo, float hi) { typedef __bf16 b2 __attribute__((ext_vector_type(2))); f32x2 v = {lo, hi}; b2 b = __builtin_convertvector(v, b2); return __builtin_bit_cast(unsigned, b); }
; DI float bflo(unsigned w) { return __uint_as_float(w << 16); }
; DI float bfhi(unsigned w) { return __uint_as_float(w & 0xffff0000u); }
;     ...
;         for (int j = 0; j < 4; ++j) { const int sp = n * 64 + t - 3 + j; const float ok = sp >= 0 ? 1.f : 0.f;
;             const u32x4 xv = xin[which * 4 + j];
;             const f32x4 w0 = *(const f32x4*)(conv_w + j * 1536 + col) * ok, w1 = *(const f32x4*)(conv_w + j * 1536 + col + 4) * ok;
;             acc[0] += w0[0] * bflo(xv.x); acc[1] += w0[1] * bfhi(xv.x); acc[2] += w0[2] * bflo(xv.y); acc[3] += w0[3] * bfhi(xv.y);
;             acc[4] += w1[0] * bflo(xv.z); acc[5] += w1[1] * bfhi(xv.z); acc[6] += w1[2] * bflo(xv.w); acc[7] += w1[3] * bfhi(xv.w); }
; #pragma unroll
;         for (int e = 0; e < 8; ++e) acc[e] = silu_f(acc[e]);
;         if (which == 2) { LAS float* dst = vc + t * 68 + cg8 * 8; *(LAS f32x4*)dst = (f32x4){acc[0], acc[1], acc[2], acc[3]}; *(LAS f32x4*)(dst + 4) = (f32x4){acc[4], acc[5], acc[6], acc[7]}; }
;         else {
;             float ss = (acc[0] * acc[0] + acc[1] * acc[1]) + (acc[2] * acc[2] + acc[3] * acc[3]) + (acc[4] * acc[4] + acc[5] * acc[5]) + (acc[6] * acc[6] + acc[7] * acc[7]);
;             ss += __shfl_xor(ss, 1); ss += __shfl_xor(ss, 2); ss += __shfl_xor(ss, 4);
;             const float sc = (which ? 1.0f : 0.125f) * __builtin_amdgcn_rsqf(ss + 1e-6f);
;             const f32x4 y0 = (f32x4){acc[0], acc[1], acc[2], acc[3]} * sc, y1 = (f32x4){acc[4], acc[5], acc[6], acc[7]} * sc;
;             LAS float* dst = (which ? kc : qc) + t * 68 + cg8 * 8; *(LAS f32x4*)dst = y0; *(LAS f32x4*)(dst + 4) = y1;
;             u32x4 hh; hh.x = pk2(y0[0], y0[1]); hh.y = pk2(y0[2], y0[3]); hh.z = pk2(y1[0], y1[1]); hh.w = pk2(y1[2], y1[3]);
;             u32x4 lo; lo.x = pk2(y0[0] - bflo(hh.x), y0[1] - bfhi(hh.x)); lo.y = pk2(y0[2] - bflo(hh.y), y0[3] - bfhi(hh.y)); lo.z = pk2(y1[0] - bflo(hh.z), y1[1] - bfhi(hh.z)); lo.w = pk2(y1[2] - bflo(hh.w), y1[3] - bfhi(hh.w));
;             *(LAS u32x4*)((which ? KH : QH) + t * 72 + cg8 * 8) = hh; *(LAS u32x4*)((which ? KL : QL) + t * 72 + cg8 * 8) = lo; }
	v_add_f32_e32 v8, v8, v9
	ds_bpermute_b32 v9, v102, v8
	s_waitcnt lgkmcnt(0)
	v_add_f32_e32 v8, v8, v9
	ds_bpermute_b32 v9, v103, v8
	s_waitcnt lgkmcnt(0)
	v_add_f32_e32 v8, v8, v9
	v_add_f32_e32 v8, 0x358637bd, v8
	v_rsq_f32_e32 v8, v8
	s_nop 0
	v_mul_f32_e32 v32, 0x3e000000, v8
	v_pk_mul_f32 v[10:11], v[20:21], v[32:33] op_sel_hi:[1,0]
	v_pk_mul_f32 v[8:9], v[28:29], v[32:33] op_sel_hi:[1,0]
	v_pk_mul_f32 v[18:19], v[12:13], v[32:33] op_sel_hi:[1,0]
	v_pk_mul_f32 v[16:17], v[30:31], v[32:33] op_sel_hi:[1,0]
	ds_write_b128 v112, v[8:11]
	ds_write_b128 v112, v[16:19] offset:16
	v_cvt_pk_bf16_f32 v8, v8, v9
	v_cvt_pk_bf16_f32 v9, v10, v11
	v_cvt_pk_bf16_f32 v10, v16, v17
	v_cvt_pk_bf16_f32 v11, v18, v19
	v_lshlrev_b32_e32 v16, 16, v8
	v_and_b32_e32 v17, 0xffff0000, v8
	v_lshlrev_b32_e32 v18, 16, v9
	v_and_b32_e32 v19, 0xffff0000, v9
	v_pk_fma_f32 v[16:17], v[28:29], v[32:33], v[16:17] op_sel_hi:[1,0,1] neg_lo:[0,0,1] neg_hi:[0,0,1]
	v_pk_fma_f32 v[18:19], v[20:21], v[32:33], v[18:19] op_sel_hi:[1,0,1] neg_lo:[0,0,1] neg_hi:[0,0,1]
	v_cvt_pk_bf16_f32 v16, v16, v17
	v_cvt_pk_bf16_f32 v17, v18, v19
	v_lshlrev_b32_e32 v18, 16, v10
	v_and_b32_e32 v19, 0xffff0000, v10
	v_lshlrev_b32_e32 v20, 16, v11
	v_and_b32_e32 v21, 0xffff0000, v11
	v_pk_fma_f32 v[18:19], v[30:31], v[32:33], v[18:19] op_sel_hi:[1,0,1] neg_lo:[0,0,1] neg_hi:[0,0,1]
	v_pk_fma_f32 v[12:13], v[12:13], v[32:33], v[20:21] op_sel_hi:[1,0,1] neg_lo:[0,0,1] neg_hi:[0,0,1]
	v_cvt_pk_bf16_f32 v18, v18, v19
	v_cvt_pk_bf16_f32 v19, v12, v13
	ds_write_b128 v113, v[8:11]
	ds_write_b128 v114, v[16:19]
	ds_read_b128 v[8:11], v255 offset:256
	ds_read_b128 v[16:19], v255 offset:272
	s_waitcnt lgkmcnt(0)
	v_pk_mul_f32 v[8:9], v[26:27], v[8:9] op_sel_hi:[0,1]
	s_waitcnt lgkmcnt(0)
	v_pk_mul_f32 v[32:33], v[26:27], v[16:17] op_sel_hi:[0,1]
	v_lshl_add_u64 v[16:17], v[14:15], 0, s[16:17]
	s_movk_i32 s16, 0x2000
	v_add_co_u32_e32 v98, vcc, s16, v14
	v_pk_mul_f32 v[12:13], v[26:27], v[18:19] op_sel_hi:[0,1]
	s_nop 0
	v_addc_co_u32_e32 v99, vcc, 0, v15, vcc
	ds_read_b128 v[18:21], v255 offset:1024
	ds_read_b128 v[28:31], v255 offset:1040
	s_mov_b64 s[16:17], 0x3800
	v_lshl_add_u64 v[16:17], v[14:15], 0, s[16:17]
	s_mov_b64 s[16:17], 0x5000
	v_lshl_add_u64 v[196:197], v[14:15], 0, s[16:17]
	s_movk_i32 s16, 0x5000
	v_pk_fma_f32 v[8:9], v[8:9], v[208:209], 0 op_sel_hi:[1,1,0]
	v_lshlrev_b32_e32 v208, 16, v62
	v_and_b32_e32 v209, 0xffff0000, v62
	v_pk_mul_f32 v[10:11], v[26:27], v[10:11] op_sel_hi:[0,1]
	s_waitcnt lgkmcnt(0)
	v_pk_mul_f32 v[18:19], v[24:25], v[18:19] op_sel_hi:[0,1]
	s_waitcnt lgkmcnt(0)
	v_pk_mul_f32 v[200:201], v[24:25], v[30:31] op_sel_hi:[0,1]
	v_pk_mul_f32 v[204:205], v[24:25], v[28:29] op_sel_hi:[0,1]
	ds_read_b128 v[28:31], v255 offset:1792
	ds_read_b128 v[94:97], v255 offset:1808
	v_add_co_u32_e32 v16, vcc, s16, v14
	v_pk_fma_f32 v[8:9], v[18:19], v[208:209], v[8:9]
	s_nop 0
	v_addc_co_u32_e32 v17, vcc, 0, v15, vcc
	v_lshlrev_b32_e32 v18, 16, v50
	v_and_b32_e32 v19, 0xffff0000, v50
	v_pk_mul_f32 v[20:21], v[24:25], v[20:21] op_sel_hi:[0,1]
	s_mov_b64 s[16:17], 0x1000
	s_andn2_b64 vcc, exec, s[46:47]
	s_waitcnt lgkmcnt(0)
	v_pk_mul_f32 v[28:29], v[22:23], v[28:29] op_sel_hi:[0,1]
	s_waitcnt lgkmcnt(0)
	v_pk_mul_f32 v[6:7], v[22:23], v[96:97] op_sel_hi:[0,1]
	v_pk_mul_f32 v[206:207], v[22:23], v[94:95] op_sel_hi:[0,1]
	ds_read_b128 v[94:97], v255 offset:2560
	s_nop 0
	ds_read_b128 v[196:199], v255 offset:2576
	v_pk_fma_f32 v[8:9], v[28:29], v[18:19], v[8:9]
	v_lshlrev_b32_e32 v18, 16, v66
	v_and_b32_e32 v19, 0xffff0000, v66
	v_pk_mul_f32 v[30:31], v[22:23], v[30:31] op_sel_hi:[0,1]
	s_waitcnt lgkmcnt(0)
	v_pk_fma_f32 v[8:9], v[94:95], v[18:19], v[8:9]
	s_nop 0
	v_mul_f32_e32 v18, 0xbfb8aa3b, v8
	v_mul_f32_e32 v19, 0xbfb8aa3b, v9
	v_exp_f32_e32 v18, v18
	v_exp_f32_e32 v19, v19
	v_add_f32_e32 v18, 1.0, v18
	v_add_f32_e32 v19, 1.0, v19
	v_rcp_f32_e32 v18, v18
	v_rcp_f32_e32 v19, v19
	s_nop 0
	v_pk_mul_f32 v[18:19], v[8:9], v[18:19]
	v_lshlrev_b32_e32 v8, 16, v55
	v_and_b32_e32 v9, 0xffff0000, v55
	v_pk_fma_f32 v[8:9], v[10:11], v[8:9], 0 op_sel_hi:[1,1,0]
	v_lshlrev_b32_e32 v10, 16, v63
	v_and_b32_e32 v11, 0xffff0000, v63
	v_pk_fma_f32 v[8:9], v[20:21], v[10:11], v[8:9]
	v_lshlrev_b32_e32 v10, 16, v51
	v_and_b32_e32 v11, 0xffff0000, v51
	v_pk_fma_f32 v[8:9], v[30:31], v[10:11], v[8:9]
	v_lshlrev_b32_e32 v10, 16, v67
	v_and_b32_e32 v11, 0xffff0000, v67
	v_pk_fma_f32 v[8:9], v[96:97], v[10:11], v[8:9]
	s_nop 0
	v_mul_f32_e32 v10, 0xbfb8aa3b, v8
	v_mul_f32_e32 v11, 0xbfb8aa3b, v9
	v_exp_f32_e32 v10, v10
	v_exp_f32_e32 v11, v11
	v_add_f32_e32 v10, 1.0, v10
	v_add_f32_e32 v11, 1.0, v11
	v_rcp_f32_e32 v10, v10
	v_rcp_f32_e32 v11, v11
	s_nop 0
	v_pk_mul_f32 v[20:21], v[8:9], v[10:11]
	v_lshlrev_b32_e32 v8, 16, v56
	v_and_b32_e32 v9, 0xffff0000, v56
	v_pk_fma_f32 v[8:9], v[32:33], v[8:9], 0 op_sel_hi:[1,1,0]
	v_lshlrev_b32_e32 v10, 16, v64
	v_and_b32_e32 v11, 0xffff0000, v64
	v_pk_fma_f32 v[8:9], v[204:205], v[10:11], v[8:9]
	v_lshlrev_b32_e32 v10, 16, v52
	v_and_b32_e32 v11, 0xffff0000, v52
	v_pk_fma_f32 v[8:9], v[206:207], v[10:11], v[8:9]
	v_lshlrev_b32_e32 v10, 16, v68
	v_and_b32_e32 v11, 0xffff0000, v68
	s_waitcnt lgkmcnt(0)
; #define LAS __attribute__((address_space(3)))
; DI float bflo(unsigned w) { return __uint_as_float(w << 16); }
; DI float bfhi(unsigned w) { return __uint_as_float(w & 0xffff0000u); }
;     ...
;     for (int which = 0; which < 3; ++which) {
;         const int t = tid >> 3, cg8 = tid & 7; const int col = which * 512 + h * 64 + cg8 * 8;
;         float acc[8];
; #pragma unroll
;         for (int e = 0; e < 8; ++e) acc[e] = 0.f;
; #pragma unroll
;         for (int j = 0; j < 4; ++j) { const int sp = n * 64 + t - 3 + j; const float ok = sp >= 0 ? 1.f : 0.f;
;             const u32x4 xv = xin[which * 4 + j];
;             const f32x4 w0 = *(const f32x4*)(conv_w + j * 1536 + col) * ok, w1 = *(const f32x4*)(conv_w + j * 1536 + col + 4) * ok;
;             acc[0] += w0[0] * bflo(xv.x); acc[1] += w0[1] * bfhi(xv.x); acc[2] += w0[2] * bflo(xv.y); acc[3] += w0[3] * bfhi(xv.y);
;             acc[4] += w1[0] * bflo(xv.z); acc[5] += w1[1] * bfhi(xv.z); acc[6] += w1[2] * bflo(xv.w); acc[7] += w1[3] * bfhi(xv.w); }
; #pragma unroll
;         for (int e = 0; e < 8; ++e) acc[e] = silu_f(acc[e]);
;         if (which == 2) { LAS float* dst = vc + t * 68 + cg8 * 8; *(LAS f32x4*)dst = (f32x4){acc[0], acc[1], acc[2], acc[3]}; *(LAS f32x4*)(dst + 4) = (f32x4){acc[4], acc[5], acc[6], acc[7]}; }
;         else {
;             float ss = (acc[0] * acc[0] + acc[1] * acc[1]) + (acc[2] * acc[2] + acc[3] * acc[3]) + (acc[4] * acc[4] + acc[5] * acc[5]) + (acc[6] * acc[6] + acc[7] * acc[7]);
;             ss += __shfl_xor(ss, 1); ss += __shfl_xor(ss, 2); ss += __shfl_xor(ss, 4);
;             const float sc = (which ? 1.0f : 0.125f) * __builtin_amdgcn_rsqf(ss + 1e-6f);
;             const f32x4 y0 = (f32x4){acc[0], acc[1], acc[2], acc[3]} * sc, y1 = (f32x4){acc[4], acc[5], acc[6], acc[7]} * sc;
;             LAS float* dst = (which ? kc : qc) + t * 68 + cg8 * 8; *(LAS f32x4*)dst = y0; *(LAS f32x4*)(dst + 4) = y1;
;             u32x4 hh; hh.x = pk2(y0[0], y0[1]); hh.y = pk2(y0[2], y0[3]); hh.z = pk2(y1[0], y1[1]); hh.w = pk2(y1[2], y1[3]);
;             u32x4 lo; lo.x = pk2(y0[0] - bflo(hh.x), y0[1] - bfhi(hh.x)); lo.y = pk2(y0[2] - bflo(hh.y), y0[3] - bfhi(hh.y)); lo.z = pk2(y1[0] - bflo(hh.z), y1[1] - bfhi(hh.z)); lo.w = pk2(y1[2] - bflo(hh.w), y1[3] - bfhi(hh.w));
;             *(LAS u32x4*)((which ? KH : QH) + t * 72 + cg8 * 8) = hh; *(LAS u32x4*)((which ? KL : QL) + t * 72 + cg8 * 8) = lo; }
	v_pk_fma_f32 v[8:9], v[196:197], v[10:11], v[8:9]
	s_nop 0
	v_mul_f32_e32 v10, 0xbfb8aa3b, v8
	v_mul_f32_e32 v11, 0xbfb8aa3b, v9
	v_exp_f32_e32 v10, v10
	v_exp_f32_e32 v11, v11
	v_add_f32_e32 v10, 1.0, v10
	v_add_f32_e32 v11, 1.0, v11
	v_rcp_f32_e32 v10, v10
	v_rcp_f32_e32 v11, v11
	s_nop 0
	v_pk_mul_f32 v[28:29], v[8:9], v[10:11]
	v_lshlrev_b32_e32 v8, 16, v57
	v_and_b32_e32 v9, 0xffff0000, v57
	v_pk_fma_f32 v[8:9], v[12:13], v[8:9], 0 op_sel_hi:[1,1,0]
	v_lshlrev_b32_e32 v10, 16, v65
	v_and_b32_e32 v11, 0xffff0000, v65
	v_pk_fma_f32 v[8:9], v[200:201], v[10:11], v[8:9]
	v_lshlrev_b32_e32 v10, 16, v53
	v_and_b32_e32 v11, 0xffff0000, v53
	v_pk_fma_f32 v[6:7], v[6:7], v[10:11], v[8:9]
	v_lshlrev_b32_e32 v8, 16, v69
	v_and_b32_e32 v9, 0xffff0000, v69
	v_pk_fma_f32 v[6:7], v[198:199], v[8:9], v[6:7]
	v_mov_b32_e32 v11, v29
	v_mul_f32_e32 v8, 0xbfb8aa3b, v7
	v_exp_f32_e32 v8, v8
	s_nop 0
	v_add_f32_e32 v8, 1.0, v8
	v_rcp_f32_e32 v9, v8
	v_mul_f32_e32 v8, 0xbfb8aa3b, v6
	v_exp_f32_e32 v8, v8
	s_nop 0
	v_add_f32_e32 v8, 1.0, v8
	v_rcp_f32_e32 v8, v8
	s_nop 0
	v_pk_mul_f32 v[30:31], v[6:7], v[8:9]
	v_mov_b32_e32 v8, v19
	v_mov_b32_e32 v9, v21
	v_mov_b32_e32 v6, v18
	v_mov_b32_e32 v7, v20
	v_pk_mul_f32 v[8:9], v[8:9], v[8:9]
	v_mov_b32_e32 v10, v31
	v_pk_fma_f32 v[6:7], v[6:7], v[6:7], v[8:9]
	v_mov_b32_e32 v8, v30
	v_mov_b32_e32 v9, v28
	v_pk_mul_f32 v[10:11], v[10:11], v[10:11]
	v_add_f32_e32 v6, v6, v7
	v_pk_fma_f32 v[8:9], v[8:9], v[8:9], v[10:11]
	s_nop 0
	v_add_f32_e32 v6, v9, v6
	v_add_f32_e32 v6, v8, v6
	ds_bpermute_b32 v7, v101, v6
	s_waitcnt lgkmcnt(0)
	v_add_f32_e32 v6, v6, v7
	ds_bpermute_b32 v7, v102, v6
	s_waitcnt lgkmcnt(0)
	v_add_f32_e32 v6, v6, v7
	ds_bpermute_b32 v7, v103, v6
	s_waitcnt lgkmcnt(0)
	v_add_f32_e32 v6, v6, v7
	v_add_f32_e32 v6, 0x358637bd, v6
	v_rsq_f32_e32 v32, v6
	s_nop 0
	v_pk_mul_f32 v[8:9], v[20:21], v[32:33] op_sel_hi:[1,0]
	v_pk_mul_f32 v[6:7], v[18:19], v[32:33] op_sel_hi:[1,0]
	v_pk_mul_f32 v[12:13], v[30:31], v[32:33] op_sel_hi:[1,0]
	v_pk_mul_f32 v[10:11], v[28:29], v[32:33] op_sel_hi:[1,0]
	ds_write_b128 v112, v[6:9] offset:17408
	ds_write_b128 v112, v[10:13] offset:17424
	v_cvt_pk_bf16_f32 v6, v6, v7
	v_cvt_pk_bf16_f32 v7, v8, v9
	v_cvt_pk_bf16_f32 v8, v10, v11
	v_cvt_pk_bf16_f32 v9, v12, v13
	v_lshlrev_b32_e32 v10, 16, v6
	v_and_b32_e32 v11, 0xffff0000, v6
	v_lshlrev_b32_e32 v12, 16, v7
	v_and_b32_e32 v13, 0xffff0000, v7
	v_pk_fma_f32 v[10:11], v[18:19], v[32:33], v[10:11] op_sel_hi:[1,0,1] neg_lo:[0,0,1] neg_hi:[0,0,1]
	v_pk_fma_f32 v[12:13], v[20:21], v[32:33], v[12:13] op_sel_hi:[1,0,1] neg_lo:[0,0,1] neg_hi:[0,0,1]
	v_cvt_pk_bf16_f32 v10, v10, v11
	v_cvt_pk_bf16_f32 v11, v12, v13
	v_lshlrev_b32_e32 v12, 16, v8
	v_and_b32_e32 v13, 0xffff0000, v8
	v_lshlrev_b32_e32 v18, 16, v9
	v_and_b32_e32 v19, 0xffff0000, v9
	v_pk_fma_f32 v[12:13], v[28:29], v[32:33], v[12:13] op_sel_hi:[1,0,1] neg_lo:[0,0,1] neg_hi:[0,0,1]
	v_pk_fma_f32 v[18:19], v[30:31], v[32:33], v[18:19] op_sel_hi:[1,0,1] neg_lo:[0,0,1] neg_hi:[0,0,1]
	v_cvt_pk_bf16_f32 v12, v12, v13
	v_cvt_pk_bf16_f32 v13, v18, v19
	ds_write_b128 v115, v[6:9]
	ds_write_b128 v116, v[10:13]
	v_lshl_add_u64 v[10:11], v[14:15], 0, s[16:17]
	ds_read_b128 v[6:9], v255 offset:512
	s_nop 0
	ds_read_b128 v[10:13], v255 offset:528
	s_mov_b64 s[16:17], 0x2800
	v_lshl_add_u64 v[2:3], v[14:15], 0, s[16:17]
	s_mov_b64 s[16:17], 0x5800
	s_waitcnt lgkmcnt(0)
	v_pk_mul_f32 v[6:7], v[26:27], v[6:7] op_sel_hi:[0,1]
	s_waitcnt lgkmcnt(0)
	v_pk_mul_f32 v[28:29], v[26:27], v[12:13] op_sel_hi:[0,1]
	v_pk_mul_f32 v[94:95], v[26:27], v[10:11] op_sel_hi:[0,1]
	ds_read_b128 v[10:13], v255 offset:1280
	ds_read_b128 v[18:21], v255 offset:1296
	v_pk_mul_f32 v[8:9], v[26:27], v[8:9] op_sel_hi:[0,1]
	s_waitcnt lgkmcnt(0)
	v_pk_mul_f32 v[10:11], v[24:25], v[10:11] op_sel_hi:[0,1]
	s_waitcnt lgkmcnt(0)
	v_pk_mul_f32 v[96:97], v[24:25], v[18:19] op_sel_hi:[0,1]
	v_lshl_add_u64 v[18:19], v[14:15], 0, s[62:63]
	v_pk_mul_f32 v[30:31], v[24:25], v[20:21] op_sel_hi:[0,1]
	ds_read_b128 v[2:5], v255 offset:2048
	s_nop 0
	ds_read_b128 v[18:21], v255 offset:2064
	v_pk_mul_f32 v[12:13], v[24:25], v[12:13] op_sel_hi:[0,1]
	s_waitcnt lgkmcnt(0)
	v_pk_mul_f32 v[4:5], v[22:23], v[4:5] op_sel_hi:[0,1]
	s_waitcnt lgkmcnt(0)
	v_pk_mul_f32 v[98:99], v[22:23], v[18:19] op_sel_hi:[0,1]
	v_lshl_add_u64 v[18:19], v[14:15], 0, s[16:17]
	v_pk_mul_f32 v[32:33], v[22:23], v[20:21] op_sel_hi:[0,1]
	ds_read_b128 v[14:17], v255 offset:2816
	s_nop 0
	ds_read_b128 v[18:21], v255 offset:2832
	v_pk_mul_f32 v[2:3], v[22:23], v[2:3] op_sel_hi:[0,1]
	v_lshlrev_b32_e32 v22, 16, v34
	v_and_b32_e32 v23, 0xffff0000, v34
	v_pk_fma_f32 v[6:7], v[6:7], v[22:23], 0 op_sel_hi:[1,1,0]
	v_lshlrev_b32_e32 v22, 16, v38
	v_and_b32_e32 v23, 0xffff0000, v38
	v_pk_fma_f32 v[6:7], v[10:11], v[22:23], v[6:7]
	v_lshlrev_b32_e32 v10, 16, v42
	v_and_b32_e32 v11, 0xffff0000, v42
	v_pk_fma_f32 v[2:3], v[2:3], v[10:11], v[6:7]
	v_lshlrev_b32_e32 v10, 16, v35
	v_and_b32_e32 v11, 0xffff0000, v35
	v_pk_fma_f32 v[8:9], v[8:9], v[10:11], 0 op_sel_hi:[1,1,0]
	v_lshlrev_b32_e32 v10, 16, v39
	v_and_b32_e32 v11, 0xffff0000, v39
	v_lshlrev_b32_e32 v6, 16, v46
	v_and_b32_e32 v7, 0xffff0000, v46
	v_pk_fma_f32 v[8:9], v[12:13], v[10:11], v[8:9]
	v_lshlrev_b32_e32 v10, 16, v43
	v_and_b32_e32 v11, 0xffff0000, v43
	v_pk_fma_f32 v[4:5], v[4:5], v[10:11], v[8:9]
	v_lshlrev_b32_e32 v8, 16, v47
	v_and_b32_e32 v9, 0xffff0000, v47
	v_lshlrev_b32_e32 v10, 16, v37
	v_and_b32_e32 v11, 0xffff0000, v37
	v_pk_fma_f32 v[10:11], v[28:29], v[10:11], 0 op_sel_hi:[1,1,0]
	v_lshlrev_b32_e32 v12, 16, v41
	v_and_b32_e32 v13, 0xffff0000, v41
	v_pk_fma_f32 v[10:11], v[30:31], v[12:13], v[10:11]
	v_lshlrev_b32_e32 v12, 16, v45
	v_and_b32_e32 v13, 0xffff0000, v45
	v_pk_fma_f32 v[10:11], v[32:33], v[12:13], v[10:11]
	v_lshlrev_b32_e32 v12, 16, v49
	v_and_b32_e32 v13, 0xffff0000, v49
	s_waitcnt lgkmcnt(0)
; #define LAS __attribute__((address_space(3)))
; DI float bflo(unsigned w) { return __uint_as_float(w << 16); }
; DI float bfhi(unsigned w) { return __uint_as_float(w & 0xffff0000u); }
; DI float silu_f(float g) { return g * frcp(1.f + fexp2(-1.4426950408889634f * g)); }
;     ...
;         for (int j = 0; j < 4; ++j) { const int sp = n * 64 + t - 3 + j; const float ok = sp >= 0 ? 1.f : 0.f;
;             const u32x4 xv = xin[which * 4 + j];
;             const f32x4 w0 = *(const f32x4*)(conv_w + j * 1536 + col) * ok, w1 = *(const f32x4*)(conv_w + j * 1536 + col + 4) * ok;
;             acc[0] += w0[0] * bflo(xv.x); acc[1] += w0[1] * bfhi(xv.x); acc[2] += w0[2] * bflo(xv.y); acc[3] += w0[3] * bfhi(xv.y);
;             acc[4] += w1[0] * bflo(xv.z); acc[5] += w1[1] * bfhi(xv.z); acc[6] += w1[2] * bflo(xv.w); acc[7] += w1[3] * bfhi(xv.w); }
; #pragma unroll
;         for (int e = 0; e < 8; ++e) acc[e] = silu_f(acc[e]);
;         if (which == 2) { LAS float* dst = vc + t * 68 + cg8 * 8; *(LAS f32x4*)dst = (f32x4){acc[0], acc[1], acc[2], acc[3]}; *(LAS f32x4*)(dst + 4) = (f32x4){acc[4], acc[5], acc[6], acc[7]}; }
	v_pk_fma_f32 v[2:3], v[14:15], v[6:7], v[2:3]
	s_nop 0
	v_mul_f32_e32 v6, 0xbfb8aa3b, v2
	v_mul_f32_e32 v7, 0xbfb8aa3b, v3
	v_pk_fma_f32 v[4:5], v[16:17], v[8:9], v[4:5]
	v_exp_f32_e32 v6, v6
	v_exp_f32_e32 v7, v7
	v_mul_f32_e32 v8, 0xbfb8aa3b, v4
	v_mul_f32_e32 v9, 0xbfb8aa3b, v5
	v_exp_f32_e32 v8, v8
	v_exp_f32_e32 v9, v9
	v_add_f32_e32 v6, 1.0, v6
	v_add_f32_e32 v7, 1.0, v7
	v_rcp_f32_e32 v6, v6
	v_rcp_f32_e32 v7, v7
	v_add_f32_e32 v8, 1.0, v8
	v_add_f32_e32 v9, 1.0, v9
	v_rcp_f32_e32 v8, v8
	v_rcp_f32_e32 v9, v9
	s_waitcnt lgkmcnt(0)
	v_pk_fma_f32 v[10:11], v[20:21], v[12:13], v[10:11]
	v_pk_mul_f32 v[2:3], v[2:3], v[6:7]
	v_mul_f32_e32 v12, 0xbfb8aa3b, v11
	v_lshlrev_b32_e32 v6, 16, v36
	v_and_b32_e32 v7, 0xffff0000, v36
	v_exp_f32_e32 v12, v12
	v_pk_mul_f32 v[4:5], v[4:5], v[8:9]
	v_pk_fma_f32 v[6:7], v[94:95], v[6:7], 0 op_sel_hi:[1,1,0]
	v_lshlrev_b32_e32 v8, 16, v40
	v_and_b32_e32 v9, 0xffff0000, v40
	v_pk_fma_f32 v[6:7], v[96:97], v[8:9], v[6:7]
	v_lshlrev_b32_e32 v8, 16, v44
	v_and_b32_e32 v9, 0xffff0000, v44
	v_pk_fma_f32 v[6:7], v[98:99], v[8:9], v[6:7]
	v_lshlrev_b32_e32 v8, 16, v48
	v_and_b32_e32 v9, 0xffff0000, v48
	v_pk_fma_f32 v[6:7], v[18:19], v[8:9], v[6:7]
	v_add_f32_e32 v12, 1.0, v12
	v_mul_f32_e32 v8, 0xbfb8aa3b, v6
	v_mul_f32_e32 v9, 0xbfb8aa3b, v7
	v_rcp_f32_e32 v13, v12
	v_mul_f32_e32 v12, 0xbfb8aa3b, v10
	v_exp_f32_e32 v8, v8
	v_exp_f32_e32 v9, v9
	v_exp_f32_e32 v12, v12
	v_add_f32_e32 v8, 1.0, v8
	v_add_f32_e32 v9, 1.0, v9
	v_add_f32_e32 v12, 1.0, v12
	v_rcp_f32_e32 v8, v8
	v_rcp_f32_e32 v9, v9
	v_rcp_f32_e32 v12, v12
	v_pk_mul_f32 v[6:7], v[6:7], v[8:9]
	v_pk_mul_f32 v[8:9], v[10:11], v[12:13]
	ds_write_b128 v176, v[2:5] offset:34816
	ds_write_b128 v176, v[6:9] offset:34832
	s_cbranch_vccnz .LBB0_1747
; DI float bf2f(bf16_t u) { return __uint_as_float(((unsigned)u) << 16); }
;     ...
;     { const float ga = bf2f(gain), gb = bf2f(gbin);
;         const float x = ga + dt_bias[h]; const float sp = fmaxf(x, 0.f) + log1pf(expf(-fabsf(x)));
;         float gv = -expf(a_log[h]) * sp; const float bv = 1.f / (1.f + expf(-gb));
;         if (wid == 0) {
; #pragma unroll
;             for (int o = 1; o < 64; o <<= 1) { const float tt = __shfl_up(gv, o); if (lane >= o) gv += tt; }
;             gcs[lane] = gv; bet[lane] = bv; } }
	s_lshl_b32 s16, s24, 2
	v_mov_b32_e32 v2, s16
	v_readlane_b32 s4, v247, 9
	global_load_dword v3, v2, s[50:51] offset:32
	v_readlane_b32 s5, v247, 10
	v_lshlrev_b32_e32 v5, 16, v1
	v_readlane_b32 s16, v247, 21
	s_mov_b32 s16, 0xb2a5705f
	v_readlane_b32 s17, v247, 22
	v_readlane_b32 s6, v247, 11
	global_load_dword v4, v2, s[4:5] offset:32
	v_lshlrev_b32_e32 v2, 16, v100
	v_mul_f32_e32 v6, 0xbfb8aa3b, v2
	v_rndne_f32_e32 v7, v6
	v_fma_f32 v8, v2, s23, -v6
	v_sub_f32_e32 v6, v6, v7
	v_fmac_f32_e32 v8, 0xb2a5705f, v2
	v_add_f32_e32 v6, v6, v8
	v_cvt_i32_f32_e32 v7, v7
	v_exp_f32_e32 v6, v6
	v_readlane_b32 s7, v247, 12
	v_readlane_b32 s8, v247, 13
	v_readlane_b32 s9, v247, 14
	v_ldexp_f32 v6, v6, v7
	v_readlane_b32 s10, v247, 15
	v_readlane_b32 s11, v247, 16
	v_readlane_b32 s12, v247, 17
	v_readlane_b32 s13, v247, 18
	v_readlane_b32 s14, v247, 19
	v_readlane_b32 s15, v247, 20
	v_readlane_b32 s18, v247, 23
	v_readlane_b32 s19, v247, 24
	s_waitcnt vmcnt(1)
	v_mul_f32_e32 v8, 0x3fb8aa3b, v3
	v_rndne_f32_e32 v9, v8
	v_cmp_ngt_f32_e32 vcc, s3, v3
	s_waitcnt vmcnt(0)
	v_add_f32_e32 v4, v4, v5
	v_fma_f32 v5, v3, s2, -v8
	v_mul_f32_e64 v10, |v4|, s23
	v_fmac_f32_e32 v5, 0x32a5705f, v3
	v_sub_f32_e32 v8, v8, v9
	v_fma_f32 v12, |v4|, s23, -v10
	v_rndne_f32_e32 v13, v10
	v_add_f32_e32 v5, v8, v5
	v_cvt_i32_f32_e32 v9, v9
	v_fma_f32 v8, |v4|, s16, v12
	v_sub_f32_e32 v10, v10, v13
	v_exp_f32_e32 v5, v5
	v_add_f32_e32 v8, v10, v8
	v_cvt_i32_f32_e32 v12, v13
	v_exp_f32_e32 v8, v8
	v_ldexp_f32 v5, v5, v9
	v_cndmask_b32_e32 v5, 0, v5, vcc
	v_cmp_nlt_f32_e32 vcc, s64, v3
	v_ldexp_f32 v8, v8, v12
	v_max_f32_e32 v11, 0, v4
	v_cndmask_b32_e32 v3, v193, v5, vcc
	v_cmp_ngt_f32_e64 vcc, |v4|, s96
	s_mov_b32 s16, 0x3f2aaaab
	s_nop 0
	v_cndmask_b32_e32 v5, 0, v8, vcc
	v_cmp_nlt_f32_e64 vcc, |v4|, s97
	s_nop 1
	v_cndmask_b32_e32 v8, v193, v5, vcc
	v_add_f32_e32 v9, 1.0, v8
	v_cvt_f64_f32_e32 v[4:5], v9
	v_frexp_mant_f32_e32 v10, v9
	v_add_f32_e32 v12, -1.0, v9
	v_frexp_exp_i32_f64_e32 v4, v[4:5]
	v_cmp_gt_f32_e32 vcc, s16, v10
	v_sub_f32_e32 v5, v8, v12
	v_sub_f32_e32 v12, v12, v9
	v_subbrev_co_u32_e32 v4, vcc, 0, v4, vcc
	v_add_f32_e32 v10, 1.0, v12
	v_cvt_f32_i32_e32 v12, v4
	v_sub_u32_e32 v4, 0, v4
	v_add_f32_e32 v5, v5, v10
	v_ldexp_f32 v9, v9, v4
	v_ldexp_f32 v4, v5, v4
	v_add_f32_e32 v5, -1.0, v9
	v_add_f32_e32 v10, 1.0, v9
	v_add_f32_e32 v13, 1.0, v5
	v_add_f32_e32 v14, -1.0, v10
	v_mul_f32_e32 v15, 0x3f317218, v12
	v_sub_f32_e32 v13, v9, v13
	v_sub_f32_e32 v9, v9, v14
	s_mov_b32 s16, 0x3f317218
	v_fma_f32 v14, v12, s16, -v15
	v_add_f32_e32 v13, v4, v13
	v_add_f32_e32 v4, v4, v9
	v_fmac_f32_e32 v14, 0xb102e308, v12
	v_add_f32_e32 v12, v10, v4
	v_rcp_f32_e32 v17, v12
	v_add_f32_e32 v9, v5, v13
	v_add_f32_e32 v16, v15, v14
	v_sub_f32_e32 v10, v10, v12
	v_sub_f32_e32 v5, v5, v9
	v_add_f32_e32 v4, v4, v10
	v_add_f32_e32 v5, v13, v5
	v_sub_f32_e32 v10, v16, v15
	v_mul_f32_e32 v13, v9, v17
	v_sub_f32_e32 v10, v14, v10
	v_mul_f32_e32 v14, v12, v13
	v_fma_f32 v15, v13, v12, -v14
	v_fmac_f32_e32 v15, v13, v4
	v_add_f32_e32 v18, v14, v15
	v_sub_f32_e32 v19, v9, v18
	v_sub_f32_e32 v9, v9, v19
	v_sub_f32_e32 v14, v18, v14
	v_sub_f32_e32 v9, v9, v18
	v_sub_f32_e32 v14, v14, v15
	v_add_f32_e32 v5, v5, v9
	v_add_f32_e32 v5, v14, v5
	v_add_f32_e32 v9, v19, v5
	v_mul_f32_e32 v14, v17, v9
	v_sub_f32_e32 v15, v19, v9
	v_mul_f32_e32 v19, v12, v14
	v_fma_f32 v12, v14, v12, -v19
	v_add_f32_e32 v18, v13, v14
	v_fmac_f32_e32 v12, v14, v4
	v_sub_f32_e32 v13, v18, v13
	v_add_f32_e32 v4, v19, v12
	v_sub_f32_e32 v13, v14, v13
	v_sub_f32_e32 v14, v9, v4
	v_sub_f32_e32 v9, v9, v14
	v_add_f32_e32 v5, v5, v15
	v_sub_f32_e32 v15, v4, v19
	v_sub_f32_e32 v4, v9, v4
	v_sub_f32_e32 v12, v15, v12
	v_add_f32_e32 v4, v5, v4
	v_add_f32_e32 v4, v12, v4
	v_add_f32_e32 v4, v14, v4
	v_mul_f32_e32 v4, v17, v4
	v_add_f32_e32 v4, v13, v4
	v_add_f32_e32 v5, v18, v4
	v_mul_f32_e32 v12, v5, v5
	v_fmamk_f32 v14, v12, 0x3e9b6dac, v177
	v_ldexp_f32 v9, v5, 1
	v_sub_f32_e32 v13, v5, v18
	v_mul_f32_e32 v5, v5, v12
	v_fmaak_f32 v12, v12, v14, 0x3f2aaada
	v_mul_f32_e32 v5, v5, v12
	v_add_f32_e32 v12, v9, v5
	v_sub_f32_e32 v4, v4, v13
	v_sub_f32_e32 v9, v12, v9
	v_ldexp_f32 v4, v4, 1
	v_sub_f32_e32 v5, v5, v9
	v_add_f32_e32 v4, v4, v5
	v_add_f32_e32 v5, v12, v4
	v_add_f32_e32 v9, v16, v5
	v_sub_f32_e32 v12, v5, v12
	v_sub_f32_e32 v4, v4, v12
	v_sub_f32_e32 v12, v9, v16
	v_sub_f32_e32 v5, v5, v12
	v_sub_f32_e32 v12, v9, v12
	v_add_f32_e32 v13, v10, v4
	v_sub_f32_e32 v12, v16, v12
	v_sub_f32_e32 v14, v13, v10
	v_add_f32_e32 v5, v5, v12
	v_sub_f32_e32 v12, v13, v14
	v_add_f32_e32 v5, v13, v5
	v_sub_f32_e32 v10, v10, v12
	v_add_f32_e32 v12, v9, v5
	v_sub_f32_e32 v4, v4, v14
	v_sub_f32_e32 v9, v12, v9
	v_add_f32_e32 v4, v4, v10
	v_sub_f32_e32 v5, v5, v9
	v_add_f32_e32 v4, v4, v5
	s_mov_b32 s16, 0x7f800000
	v_add_f32_e32 v4, v12, v4
	v_cmp_neq_f32_e32 vcc, s16, v8
	s_mov_b32 s16, 0x33800000
	s_nop 0
	v_cndmask_b32_e32 v4, v193, v4, vcc
	v_cmp_lt_f32_e64 vcc, |v8|, s16
	s_nop 1
	v_cndmask_b32_e32 v4, v4, v8, vcc
	v_add_f32_e32 v4, v11, v4
	v_mul_f32_e64 v5, v4, -v3
	ds_bpermute_b32 v8, v104, v5
	v_cmp_nlt_f32_e32 vcc, s96, v2
	s_waitcnt lgkmcnt(0)
	v_fma_f32 v3, v4, -v3, v8
	v_cndmask_b32_e64 v3, v3, v5, s[58:59]
	ds_bpermute_b32 v4, v105, v3
	v_cndmask_b32_e32 v5, 0, v6, vcc
	v_cmp_ngt_f32_e32 vcc, s97, v2
	s_waitcnt lgkmcnt(0)
	v_add_f32_e32 v4, v3, v4
	v_cndmask_b32_e64 v3, v4, v3, s[56:57]
	ds_bpermute_b32 v4, v106, v3
	v_cndmask_b32_e32 v2, v193, v5, vcc
	v_add_f32_e32 v2, 1.0, v2
	v_div_scale_f32 v5, s[16:17], v2, v2, 1.0
	s_waitcnt lgkmcnt(0)
	v_add_f32_e32 v4, v3, v4
	v_cndmask_b32_e64 v3, v4, v3, s[74:75]
	ds_bpermute_b32 v4, v107, v3
	v_rcp_f32_e32 v6, v5
	v_div_scale_f32 v7, vcc, 1.0, v2, 1.0
	s_waitcnt lgkmcnt(0)
	v_add_f32_e32 v4, v3, v4
	v_cndmask_b32_e64 v3, v4, v3, s[76:77]
	ds_bpermute_b32 v4, v108, v3
	v_fma_f32 v8, -v5, v6, 1.0
	v_fmac_f32_e32 v6, v8, v6
	v_mul_f32_e32 v8, v7, v6
	v_fma_f32 v9, -v5, v8, v7
	s_waitcnt lgkmcnt(0)
	v_add_f32_e32 v4, v3, v4
	v_cndmask_b32_e64 v3, v4, v3, s[78:79]
	ds_bpermute_b32 v4, v109, v3
	v_fmac_f32_e32 v8, v9, v6
	v_fma_f32 v5, -v5, v8, v7
	v_div_fmas_f32 v5, v5, v6, v8
	v_div_fixup_f32 v2, v5, v2, 1.0
	s_waitcnt lgkmcnt(0)
	v_add_f32_e32 v4, v3, v4
	v_cndmask_b32_e64 v3, v4, v3, s[60:61]
	ds_write_b32 v117, v3
	ds_write_b32 v118, v2

; __global__ void __launch_bounds__(512, 2) mk_fwd(Args args) {
;     extern __shared__ __attribute__((aligned(16))) unsigned char lds_raw[];
	.amdhsa_kernel _Z6mk_fwd4Args
		.amdhsa_group_segment_fixed_size 6400
		.amdhsa_private_segment_fixed_size 0
		.amdhsa_kernarg_size 456
		.amdhsa_user_sgpr_count 2
		.amdhsa_user_sgpr_dispatch_ptr 0
		.amdhsa_user_sgpr_queue_ptr 0
		.amdhsa_user_sgpr_kernarg_segment_ptr 1
		.amdhsa_user_sgpr_dispatch_id 0
		.amdhsa_user_sgpr_kernarg_preload_length 0
		.amdhsa_user_sgpr_kernarg_preload_offset 0
		.amdhsa_user_sgpr_private_segment_size 0
		.amdhsa_uses_dynamic_stack 0
		.amdhsa_enable_private_segment 0
		.amdhsa_system_sgpr_workgroup_id_x 1
		.amdhsa_system_sgpr_workgroup_id_y 0
		.amdhsa_system_sgpr_workgroup_id_z 0
		.amdhsa_system_sgpr_workgroup_info 0
		.amdhsa_system_vgpr_workitem_id 2
		.amdhsa_next_free_vgpr 256
		.amdhsa_next_free_sgpr 102
		.amdhsa_accum_offset 256
		.amdhsa_reserve_vcc 1
		.amdhsa_float_round_mode_32 0
		.amdhsa_float_round_mode_16_64 0
		.amdhsa_float_denorm_mode_32 3
		.amdhsa_float_denorm_mode_16_64 3
		.amdhsa_dx10_clamp 1
		.amdhsa_ieee_mode 1
		.amdhsa_fp16_overflow 0
		.amdhsa_tg_split 0
		.amdhsa_exception_fp_ieee_invalid_op 0
		.amdhsa_exception_fp_denorm_src 0
		.amdhsa_exception_fp_ieee_div_zero 0
		.amdhsa_exception_fp_ieee_overflow 0
		.amdhsa_exception_fp_ieee_underflow 0
		.amdhsa_exception_fp_ieee_inexact 0
		.amdhsa_exception_int_div_zero 0
	.end_amdhsa_kernel

; __global__ void __launch_bounds__(512, 2) mk_fwd(Args args) {
;     extern __shared__ __attribute__((aligned(16))) unsigned char lds_raw[];
amdhsa.kernels:
  - .agpr_count:     0
    .args:
      - .offset:         0
        .size:           200
        .value_kind:     by_value
      - .offset:         200
        .size:           4
        .value_kind:     hidden_block_count_x
      - .offset:         204
        .size:           4
        .value_kind:     hidden_block_count_y
      - .offset:         208
        .size:           4
        .value_kind:     hidden_block_count_z
      - .offset:         212
        .size:           2
        .value_kind:     hidden_group_size_x
      - .offset:         214
        .size:           2
        .value_kind:     hidden_group_size_y
      - .offset:         216
        .size:           2
        .value_kind:     hidden_group_size_z
      - .offset:         218
        .size:           2
        .value_kind:     hidden_remainder_x
      - .offset:         220
        .size:           2
        .value_kind:     hidden_remainder_y
      - .offset:         222
        .size:           2
        .value_kind:     hidden_remainder_z
      - .offset:         240
        .size:           8
        .value_kind:     hidden_global_offset_x
      - .offset:         248
        .size:           8
        .value_kind:     hidden_global_offset_y
      - .offset:         256
        .size:           8
        .value_kind:     hidden_global_offset_z
      - .offset:         264
        .size:           2
        .value_kind:     hidden_grid_dims
      - .offset:         288
        .size:           8
        .value_kind:     hidden_multigrid_sync_arg
      - .offset:         320
        .size:           4
        .value_kind:     hidden_dynamic_lds_size
    .group_segment_fixed_size: 6400
    .kernarg_segment_align: 8
    .kernarg_segment_size: 456
    .language:       OpenCL C
    .language_version:
      - 2
      - 0
    .max_flat_workgroup_size: 512
    .name:           _Z6mk_fwd4Args
    .private_segment_fixed_size: 0
    .sgpr_count:     108
    .sgpr_spill_count: 172
    .symbol:         _Z6mk_fwd4Args.kd
    .uniform_work_group_size: 1
    .uses_dynamic_stack: false
    .vgpr_count:     256
    .vgpr_spill_count: 0
    .wavefront_size: 64
